# k10 + rewritten diff combine/sub-LN row loop: loads hoisted and pipelined one 4-row group ahead, DPP+readlane wave reduction instead of ds_bpermute, saddr addressing
# speedup vs baseline: 1.0044x; 1.0044x over previous
.LBB0_410:
	s_add_u32 s96, s54, 0x13000000
	s_addc_u32 s97, s55, 0
	s_add_u32 s98, s54, 0x39300000
	s_addc_u32 s99, s55, 0
	s_add_u32 s4, s96, 0x1000
	s_addc_u32 s5, s97, 0
	s_add_u32 s6, s98, 0x1000
	s_addc_u32 s7, s99, 0
	global_load_dwordx2 v[40:41], v184, s[4:5] offset:-4096
	global_load_dwordx2 v[42:43], v184, s[6:7] offset:-4096
	global_load_dwordx2 v[44:45], v184, s[4:5]
	global_load_dwordx2 v[46:47], v184, s[6:7]
	s_add_u32 s4, s4, 0x2000
	s_addc_u32 s5, s5, 0
	s_add_u32 s6, s6, 0x2000
	s_addc_u32 s7, s7, 0
	global_load_dwordx2 v[48:49], v184, s[4:5] offset:-4096
	global_load_dwordx2 v[50:51], v184, s[6:7] offset:-4096
	global_load_dwordx2 v[52:53], v184, s[4:5]
	global_load_dwordx2 v[54:55], v184, s[6:7]
	s_add_u32 s4, s96, 0x5000
	s_addc_u32 s5, s97, 0
	s_add_u32 s6, s98, 0x5000
	s_addc_u32 s7, s99, 0
	global_load_dwordx2 v[56:57], v184, s[4:5] offset:-4096
	global_load_dwordx2 v[58:59], v184, s[6:7] offset:-4096
	global_load_dwordx2 v[60:61], v184, s[4:5]
	global_load_dwordx2 v[62:63], v184, s[6:7]
	s_add_u32 s4, s4, 0x2000
	s_addc_u32 s5, s5, 0
	s_add_u32 s6, s6, 0x2000
	s_addc_u32 s7, s7, 0
	global_load_dwordx2 v[64:65], v184, s[4:5] offset:-4096
	global_load_dwordx2 v[66:67], v184, s[6:7] offset:-4096
	global_load_dwordx2 v[68:69], v184, s[4:5]
	global_load_dwordx2 v[70:71], v184, s[6:7]
	s_waitcnt vmcnt(8)
	v_lshlrev_b32_e32 v8, 16, v40
	v_lshlrev_b32_e32 v19, 16, v42
	v_and_b32_e32 v29, 0xffff0000, v40
	v_and_b32_e32 v34, 0xffff0000, v42
	v_fma_f32 v20, -v18, v19, v8
	v_fma_f32 v21, -v18, v34, v29
	v_lshlrev_b32_e32 v8, 16, v41
	v_lshlrev_b32_e32 v19, 16, v43
	v_and_b32_e32 v29, 0xffff0000, v41
	v_and_b32_e32 v34, 0xffff0000, v43
	v_fma_f32 v30, -v18, v19, v8
	v_fma_f32 v31, -v18, v34, v29
	v_mul_f32_e32 v8, v21, v21
	v_mul_f32_e32 v19, v31, v31
	v_fmac_f32_e32 v8, v20, v20
	v_fmac_f32_e32 v19, v30, v30
	v_add_f32_e32 v8, v8, v19
	s_nop 1
	v_add_f32_dpp v8, v8, v8 quad_perm:[1,0,3,2] row_mask:0xf bank_mask:0xf
	s_nop 1
	v_add_f32_dpp v8, v8, v8 quad_perm:[2,3,0,1] row_mask:0xf bank_mask:0xf
	s_nop 1
	v_add_f32_dpp v8, v8, v8 row_half_mirror row_mask:0xf bank_mask:0xf
	s_nop 1
	v_add_f32_dpp v8, v8, v8 row_mirror row_mask:0xf bank_mask:0xf
	s_nop 1
	v_readlane_b32 s14, v8, 0
	v_readlane_b32 s15, v8, 16
	v_readlane_b32 s24, v8, 32
	v_readlane_b32 s25, v8, 48
	s_nop 2
	v_mov_b32_e32 v19, s15
	v_mov_b32_e32 v29, s25
	v_add_f32_e32 v19, s14, v19
	v_add_f32_e32 v29, s24, v29
	v_add_f32_e32 v8, v19, v29
	v_fmamk_f32 v8, v8, 0x3b800000, v191
	v_mul_f32_e32 v19, 0x4f800000, v8
	v_cmp_gt_f32_e32 vcc, s76, v8
	s_nop 1
	v_cndmask_b32_e32 v8, v8, v19, vcc
	v_sqrt_f32_e32 v19, v8
	s_nop 0
	v_add_u32_e32 v29, -1, v19
	v_add_u32_e32 v34, 1, v19
	v_fma_f32 v35, -v29, v19, v8
	v_fma_f32 v36, -v34, v19, v8
	v_cmp_ge_f32_e64 s[14:15], 0, v35
	s_nop 1
	v_cndmask_b32_e64 v19, v19, v29, s[14:15]
	v_cmp_lt_f32_e64 s[14:15], 0, v36
	s_nop 1
	v_cndmask_b32_e64 v19, v19, v34, s[14:15]
	v_mul_f32_e32 v29, 0x37800000, v19
	v_cndmask_b32_e32 v19, v19, v29, vcc
	v_cmp_class_f32_e32 vcc, v8, v192
	s_nop 1
	v_cndmask_b32_e32 v8, v19, v8, vcc
	v_div_scale_f32 v19, s[14:15], v8, v8, 1.0
	v_rcp_f32_e32 v34, v19
	v_div_scale_f32 v29, vcc, 1.0, v8, 1.0
	v_fma_f32 v35, -v19, v34, 1.0
	v_fmac_f32_e32 v34, v35, v34
	v_mul_f32_e32 v35, v29, v34
	v_fma_f32 v36, -v19, v35, v29
	v_fmac_f32_e32 v35, v36, v34
	v_fma_f32 v19, -v19, v35, v29
	v_div_fmas_f32 v19, v19, v34, v35
	v_div_fixup_f32 v8, v19, v8, 1.0
	v_mul_f32_e32 v20, v20, v8
	v_mul_f32_e32 v21, v21, v8
	v_mul_f32_e32 v30, v30, v8
	v_mul_f32_e32 v31, v31, v8
	v_mul_f32_e32 v20, v4, v20
	v_mul_f32_e32 v21, v5, v21
	v_mul_f32_e32 v30, v2, v30
	v_mul_f32_e32 v31, v3, v31
	v_cvt_pk_bf16_f32 v32, v20, v21
	v_cvt_pk_bf16_f32 v33, v30, v31
	s_add_i32 s14, s50, 0
	s_and_b32 s14, s14, 0xfc
	s_or_b32 s14, s14, s48
	s_mov_b32 s15, s49
	s_lshl_b64 s[14:15], s[14:15], 13
	v_lshl_add_u64 v[10:11], v[0:1], 0, s[14:15]
	global_store_dwordx2 v[10:11], v[32:33], off
	v_lshlrev_b32_e32 v8, 16, v44
	v_lshlrev_b32_e32 v19, 16, v46
	v_and_b32_e32 v29, 0xffff0000, v44
	v_and_b32_e32 v34, 0xffff0000, v46
	v_fma_f32 v20, -v18, v19, v8
	v_fma_f32 v21, -v18, v34, v29
	v_lshlrev_b32_e32 v8, 16, v45
	v_lshlrev_b32_e32 v19, 16, v47
	v_and_b32_e32 v29, 0xffff0000, v45
	v_and_b32_e32 v34, 0xffff0000, v47
	v_fma_f32 v30, -v18, v19, v8
	v_fma_f32 v31, -v18, v34, v29
	v_mul_f32_e32 v8, v21, v21
	v_mul_f32_e32 v19, v31, v31
	v_fmac_f32_e32 v8, v20, v20
	v_fmac_f32_e32 v19, v30, v30
	v_add_f32_e32 v8, v8, v19
	s_nop 1
	v_add_f32_dpp v8, v8, v8 quad_perm:[1,0,3,2] row_mask:0xf bank_mask:0xf
	s_nop 1
	v_add_f32_dpp v8, v8, v8 quad_perm:[2,3,0,1] row_mask:0xf bank_mask:0xf
	s_nop 1
	v_add_f32_dpp v8, v8, v8 row_half_mirror row_mask:0xf bank_mask:0xf
	s_nop 1
	v_add_f32_dpp v8, v8, v8 row_mirror row_mask:0xf bank_mask:0xf
	s_nop 1
	v_readlane_b32 s14, v8, 0
	v_readlane_b32 s15, v8, 16
	v_readlane_b32 s24, v8, 32
	v_readlane_b32 s25, v8, 48
	s_nop 2
	v_mov_b32_e32 v19, s15
	v_mov_b32_e32 v29, s25
	v_add_f32_e32 v19, s14, v19
	v_add_f32_e32 v29, s24, v29
	v_add_f32_e32 v8, v19, v29
	v_fmamk_f32 v8, v8, 0x3b800000, v191
	v_mul_f32_e32 v19, 0x4f800000, v8
	v_cmp_gt_f32_e32 vcc, s76, v8
	s_nop 1
	v_cndmask_b32_e32 v8, v8, v19, vcc
	v_sqrt_f32_e32 v19, v8
	s_nop 0
	v_add_u32_e32 v29, -1, v19
	v_add_u32_e32 v34, 1, v19
	v_fma_f32 v35, -v29, v19, v8
	v_fma_f32 v36, -v34, v19, v8
	v_cmp_ge_f32_e64 s[14:15], 0, v35
	s_nop 1
	v_cndmask_b32_e64 v19, v19, v29, s[14:15]
	v_cmp_lt_f32_e64 s[14:15], 0, v36
	s_nop 1
	v_cndmask_b32_e64 v19, v19, v34, s[14:15]
	v_mul_f32_e32 v29, 0x37800000, v19
	v_cndmask_b32_e32 v19, v19, v29, vcc
	v_cmp_class_f32_e32 vcc, v8, v192
	s_nop 1
	v_cndmask_b32_e32 v8, v19, v8, vcc
	v_div_scale_f32 v19, s[14:15], v8, v8, 1.0
	v_rcp_f32_e32 v34, v19
	v_div_scale_f32 v29, vcc, 1.0, v8, 1.0
	v_fma_f32 v35, -v19, v34, 1.0
	v_fmac_f32_e32 v34, v35, v34
	v_mul_f32_e32 v35, v29, v34
	v_fma_f32 v36, -v19, v35, v29
	v_fmac_f32_e32 v35, v36, v34
	v_fma_f32 v19, -v19, v35, v29
	v_div_fmas_f32 v19, v19, v34, v35
	v_div_fixup_f32 v8, v19, v8, 1.0
	v_mul_f32_e32 v20, v20, v8
	v_mul_f32_e32 v21, v21, v8
	v_mul_f32_e32 v30, v30, v8
	v_mul_f32_e32 v31, v31, v8
	v_mul_f32_e32 v20, v4, v20
	v_mul_f32_e32 v21, v5, v21
	v_mul_f32_e32 v30, v2, v30
	v_mul_f32_e32 v31, v3, v31
	v_cvt_pk_bf16_f32 v32, v20, v21
	v_cvt_pk_bf16_f32 v33, v30, v31
	s_add_u32 s14, s52, 0x2000
	s_addc_u32 s15, s53, 0
	global_store_dwordx2 v184, v[32:33], s[14:15]
	v_lshlrev_b32_e32 v8, 16, v48
	v_lshlrev_b32_e32 v19, 16, v50
	v_and_b32_e32 v29, 0xffff0000, v48
	v_and_b32_e32 v34, 0xffff0000, v50
	v_fma_f32 v20, -v18, v19, v8
	v_fma_f32 v21, -v18, v34, v29
	v_lshlrev_b32_e32 v8, 16, v49
	v_lshlrev_b32_e32 v19, 16, v51
	v_and_b32_e32 v29, 0xffff0000, v49
	v_and_b32_e32 v34, 0xffff0000, v51
	v_fma_f32 v30, -v18, v19, v8
	v_fma_f32 v31, -v18, v34, v29
	v_mul_f32_e32 v8, v21, v21
	v_mul_f32_e32 v19, v31, v31
	v_fmac_f32_e32 v8, v20, v20
	v_fmac_f32_e32 v19, v30, v30
	v_add_f32_e32 v8, v8, v19
	s_nop 1
	v_add_f32_dpp v8, v8, v8 quad_perm:[1,0,3,2] row_mask:0xf bank_mask:0xf
	s_nop 1
	v_add_f32_dpp v8, v8, v8 quad_perm:[2,3,0,1] row_mask:0xf bank_mask:0xf
	s_nop 1
	v_add_f32_dpp v8, v8, v8 row_half_mirror row_mask:0xf bank_mask:0xf
	s_nop 1
	v_add_f32_dpp v8, v8, v8 row_mirror row_mask:0xf bank_mask:0xf
	s_nop 1
	v_readlane_b32 s14, v8, 0
	v_readlane_b32 s15, v8, 16
	v_readlane_b32 s24, v8, 32
	v_readlane_b32 s25, v8, 48
	s_nop 2
	v_mov_b32_e32 v19, s15
	v_mov_b32_e32 v29, s25
	v_add_f32_e32 v19, s14, v19
	v_add_f32_e32 v29, s24, v29
	v_add_f32_e32 v8, v19, v29
	v_fmamk_f32 v8, v8, 0x3b800000, v191
	v_mul_f32_e32 v19, 0x4f800000, v8
	v_cmp_gt_f32_e32 vcc, s76, v8
	s_nop 1
	v_cndmask_b32_e32 v8, v8, v19, vcc
	v_sqrt_f32_e32 v19, v8
	s_nop 0
	v_add_u32_e32 v29, -1, v19
	v_add_u32_e32 v34, 1, v19
	v_fma_f32 v35, -v29, v19, v8
	v_fma_f32 v36, -v34, v19, v8
	v_cmp_ge_f32_e64 s[14:15], 0, v35
	s_nop 1
	v_cndmask_b32_e64 v19, v19, v29, s[14:15]
	v_cmp_lt_f32_e64 s[14:15], 0, v36
	s_nop 1
	v_cndmask_b32_e64 v19, v19, v34, s[14:15]
	v_mul_f32_e32 v29, 0x37800000, v19
	v_cndmask_b32_e32 v19, v19, v29, vcc
	v_cmp_class_f32_e32 vcc, v8, v192
	s_nop 1
	v_cndmask_b32_e32 v8, v19, v8, vcc
	v_div_scale_f32 v19, s[14:15], v8, v8, 1.0
	v_rcp_f32_e32 v34, v19
	v_div_scale_f32 v29, vcc, 1.0, v8, 1.0
	v_fma_f32 v35, -v19, v34, 1.0
	v_fmac_f32_e32 v34, v35, v34
	v_mul_f32_e32 v35, v29, v34
	v_fma_f32 v36, -v19, v35, v29
	v_fmac_f32_e32 v35, v36, v34
	v_fma_f32 v19, -v19, v35, v29
	v_div_fmas_f32 v19, v19, v34, v35
	v_div_fixup_f32 v8, v19, v8, 1.0
	v_mul_f32_e32 v20, v20, v8
	v_mul_f32_e32 v21, v21, v8
	v_mul_f32_e32 v30, v30, v8
	v_mul_f32_e32 v31, v31, v8
	v_mul_f32_e32 v20, v4, v20
	v_mul_f32_e32 v21, v5, v21
	v_mul_f32_e32 v30, v2, v30
	v_mul_f32_e32 v31, v3, v31
	v_cvt_pk_bf16_f32 v32, v20, v21
	v_cvt_pk_bf16_f32 v33, v30, v31
	s_add_i32 s14, s50, 2
	s_and_b32 s14, s14, 0xfe
	s_or_b32 s14, s14, s48
	s_mov_b32 s15, s49
	s_lshl_b64 s[14:15], s[14:15], 13
	v_lshl_add_u64 v[10:11], v[0:1], 0, s[14:15]
	global_store_dwordx2 v[10:11], v[32:33], off
	v_lshlrev_b32_e32 v8, 16, v52
	v_lshlrev_b32_e32 v19, 16, v54
	v_and_b32_e32 v29, 0xffff0000, v52
	v_and_b32_e32 v34, 0xffff0000, v54
	v_fma_f32 v20, -v18, v19, v8
	v_fma_f32 v21, -v18, v34, v29
	v_lshlrev_b32_e32 v8, 16, v53
	v_lshlrev_b32_e32 v19, 16, v55
	v_and_b32_e32 v29, 0xffff0000, v53
	v_and_b32_e32 v34, 0xffff0000, v55
	v_fma_f32 v30, -v18, v19, v8
	v_fma_f32 v31, -v18, v34, v29
	v_mul_f32_e32 v8, v21, v21
	v_mul_f32_e32 v19, v31, v31
	v_fmac_f32_e32 v8, v20, v20
	v_fmac_f32_e32 v19, v30, v30
	v_add_f32_e32 v8, v8, v19
	s_nop 1
	v_add_f32_dpp v8, v8, v8 quad_perm:[1,0,3,2] row_mask:0xf bank_mask:0xf
	s_nop 1
	v_add_f32_dpp v8, v8, v8 quad_perm:[2,3,0,1] row_mask:0xf bank_mask:0xf
	s_nop 1
	v_add_f32_dpp v8, v8, v8 row_half_mirror row_mask:0xf bank_mask:0xf
	s_nop 1
	v_add_f32_dpp v8, v8, v8 row_mirror row_mask:0xf bank_mask:0xf
	s_nop 1
	v_readlane_b32 s14, v8, 0
	v_readlane_b32 s15, v8, 16
	v_readlane_b32 s24, v8, 32
	v_readlane_b32 s25, v8, 48
	s_nop 2
	v_mov_b32_e32 v19, s15
	v_mov_b32_e32 v29, s25
	v_add_f32_e32 v19, s14, v19
	v_add_f32_e32 v29, s24, v29
	v_add_f32_e32 v8, v19, v29
	v_fmamk_f32 v8, v8, 0x3b800000, v191
	v_mul_f32_e32 v19, 0x4f800000, v8
	v_cmp_gt_f32_e32 vcc, s76, v8
	s_nop 1
	v_cndmask_b32_e32 v8, v8, v19, vcc
	v_sqrt_f32_e32 v19, v8
	s_nop 0
	v_add_u32_e32 v29, -1, v19
	v_add_u32_e32 v34, 1, v19
	v_fma_f32 v35, -v29, v19, v8
	v_fma_f32 v36, -v34, v19, v8
	v_cmp_ge_f32_e64 s[14:15], 0, v35
	s_nop 1
	v_cndmask_b32_e64 v19, v19, v29, s[14:15]
	v_cmp_lt_f32_e64 s[14:15], 0, v36
	s_nop 1
	v_cndmask_b32_e64 v19, v19, v34, s[14:15]
	v_mul_f32_e32 v29, 0x37800000, v19
	v_cndmask_b32_e32 v19, v19, v29, vcc
	v_cmp_class_f32_e32 vcc, v8, v192
	s_nop 1
	v_cndmask_b32_e32 v8, v19, v8, vcc
	v_div_scale_f32 v19, s[14:15], v8, v8, 1.0
	v_rcp_f32_e32 v34, v19
	v_div_scale_f32 v29, vcc, 1.0, v8, 1.0
	v_fma_f32 v35, -v19, v34, 1.0
	v_fmac_f32_e32 v34, v35, v34
	v_mul_f32_e32 v35, v29, v34
	v_fma_f32 v36, -v19, v35, v29
	v_fmac_f32_e32 v35, v36, v34
	v_fma_f32 v19, -v19, v35, v29
	v_div_fmas_f32 v19, v19, v34, v35
	v_div_fixup_f32 v8, v19, v8, 1.0
	v_mul_f32_e32 v20, v20, v8
	v_mul_f32_e32 v21, v21, v8
	v_mul_f32_e32 v30, v30, v8
	v_mul_f32_e32 v31, v31, v8
	v_mul_f32_e32 v20, v4, v20
	v_mul_f32_e32 v21, v5, v21
	v_mul_f32_e32 v30, v2, v30
	v_mul_f32_e32 v31, v3, v31
	v_cvt_pk_bf16_f32 v32, v20, v21
	v_cvt_pk_bf16_f32 v33, v30, v31
	s_add_u32 s14, s52, 0x6000
	s_addc_u32 s15, s53, 0
	global_store_dwordx2 v184, v[32:33], s[14:15]
	s_add_u32 s4, s96, 0x9000
	s_addc_u32 s5, s97, 0
	s_add_u32 s6, s98, 0x9000
	s_addc_u32 s7, s99, 0
	global_load_dwordx2 v[40:41], v184, s[4:5] offset:-4096
	global_load_dwordx2 v[42:43], v184, s[6:7] offset:-4096
	global_load_dwordx2 v[44:45], v184, s[4:5]
	global_load_dwordx2 v[46:47], v184, s[6:7]
	s_add_u32 s4, s4, 0x2000
	s_addc_u32 s5, s5, 0
	s_add_u32 s6, s6, 0x2000
	s_addc_u32 s7, s7, 0
	global_load_dwordx2 v[48:49], v184, s[4:5] offset:-4096
	global_load_dwordx2 v[50:51], v184, s[6:7] offset:-4096
	global_load_dwordx2 v[52:53], v184, s[4:5]
	global_load_dwordx2 v[54:55], v184, s[6:7]
	s_waitcnt vmcnt(12)
	v_lshlrev_b32_e32 v8, 16, v56
	v_lshlrev_b32_e32 v19, 16, v58
	v_and_b32_e32 v29, 0xffff0000, v56
	v_and_b32_e32 v34, 0xffff0000, v58
	v_fma_f32 v20, -v18, v19, v8
	v_fma_f32 v21, -v18, v34, v29
	v_lshlrev_b32_e32 v8, 16, v57
	v_lshlrev_b32_e32 v19, 16, v59
	v_and_b32_e32 v29, 0xffff0000, v57
	v_and_b32_e32 v34, 0xffff0000, v59
	v_fma_f32 v30, -v18, v19, v8
	v_fma_f32 v31, -v18, v34, v29
	v_mul_f32_e32 v8, v21, v21
	v_mul_f32_e32 v19, v31, v31
	v_fmac_f32_e32 v8, v20, v20
	v_fmac_f32_e32 v19, v30, v30
	v_add_f32_e32 v8, v8, v19
	s_nop 1
	v_add_f32_dpp v8, v8, v8 quad_perm:[1,0,3,2] row_mask:0xf bank_mask:0xf
	s_nop 1
	v_add_f32_dpp v8, v8, v8 quad_perm:[2,3,0,1] row_mask:0xf bank_mask:0xf
	s_nop 1
	v_add_f32_dpp v8, v8, v8 row_half_mirror row_mask:0xf bank_mask:0xf
	s_nop 1
	v_add_f32_dpp v8, v8, v8 row_mirror row_mask:0xf bank_mask:0xf
	s_nop 1
	v_readlane_b32 s14, v8, 0
	v_readlane_b32 s15, v8, 16
	v_readlane_b32 s24, v8, 32
	v_readlane_b32 s25, v8, 48
	s_nop 2
	v_mov_b32_e32 v19, s15
	v_mov_b32_e32 v29, s25
	v_add_f32_e32 v19, s14, v19
	v_add_f32_e32 v29, s24, v29
	v_add_f32_e32 v8, v19, v29
	v_fmamk_f32 v8, v8, 0x3b800000, v191
	v_mul_f32_e32 v19, 0x4f800000, v8
	v_cmp_gt_f32_e32 vcc, s76, v8
	s_nop 1
	v_cndmask_b32_e32 v8, v8, v19, vcc
	v_sqrt_f32_e32 v19, v8
	s_nop 0
	v_add_u32_e32 v29, -1, v19
	v_add_u32_e32 v34, 1, v19
	v_fma_f32 v35, -v29, v19, v8
	v_fma_f32 v36, -v34, v19, v8
	v_cmp_ge_f32_e64 s[14:15], 0, v35
	s_nop 1
	v_cndmask_b32_e64 v19, v19, v29, s[14:15]
	v_cmp_lt_f32_e64 s[14:15], 0, v36
	s_nop 1
	v_cndmask_b32_e64 v19, v19, v34, s[14:15]
	v_mul_f32_e32 v29, 0x37800000, v19
	v_cndmask_b32_e32 v19, v19, v29, vcc
	v_cmp_class_f32_e32 vcc, v8, v192
	s_nop 1
	v_cndmask_b32_e32 v8, v19, v8, vcc
	v_div_scale_f32 v19, s[14:15], v8, v8, 1.0
	v_rcp_f32_e32 v34, v19
	v_div_scale_f32 v29, vcc, 1.0, v8, 1.0
	v_fma_f32 v35, -v19, v34, 1.0
	v_fmac_f32_e32 v34, v35, v34
	v_mul_f32_e32 v35, v29, v34
	v_fma_f32 v36, -v19, v35, v29
	v_fmac_f32_e32 v35, v36, v34
	v_fma_f32 v19, -v19, v35, v29
	v_div_fmas_f32 v19, v19, v34, v35
	v_div_fixup_f32 v8, v19, v8, 1.0
	v_mul_f32_e32 v20, v20, v8
	v_mul_f32_e32 v21, v21, v8
	v_mul_f32_e32 v30, v30, v8
	v_mul_f32_e32 v31, v31, v8
	v_mul_f32_e32 v20, v4, v20
	v_mul_f32_e32 v21, v5, v21
	v_mul_f32_e32 v30, v2, v30
	v_mul_f32_e32 v31, v3, v31
	v_cvt_pk_bf16_f32 v32, v20, v21
	v_cvt_pk_bf16_f32 v33, v30, v31
	s_add_i32 s14, s50, 4
	s_and_b32 s14, s14, 0xfc
	s_or_b32 s14, s14, s48
	s_mov_b32 s15, s49
	s_lshl_b64 s[14:15], s[14:15], 13
	v_lshl_add_u64 v[10:11], v[0:1], 0, s[14:15]
	global_store_dwordx2 v[10:11], v[32:33], off
	v_lshlrev_b32_e32 v8, 16, v60
	v_lshlrev_b32_e32 v19, 16, v62
	v_and_b32_e32 v29, 0xffff0000, v60
	v_and_b32_e32 v34, 0xffff0000, v62
	v_fma_f32 v20, -v18, v19, v8
	v_fma_f32 v21, -v18, v34, v29
	v_lshlrev_b32_e32 v8, 16, v61
	v_lshlrev_b32_e32 v19, 16, v63
	v_and_b32_e32 v29, 0xffff0000, v61
	v_and_b32_e32 v34, 0xffff0000, v63
	v_fma_f32 v30, -v18, v19, v8
	v_fma_f32 v31, -v18, v34, v29
	v_mul_f32_e32 v8, v21, v21
	v_mul_f32_e32 v19, v31, v31
	v_fmac_f32_e32 v8, v20, v20
	v_fmac_f32_e32 v19, v30, v30
	v_add_f32_e32 v8, v8, v19
	s_nop 1
	v_add_f32_dpp v8, v8, v8 quad_perm:[1,0,3,2] row_mask:0xf bank_mask:0xf
	s_nop 1
	v_add_f32_dpp v8, v8, v8 quad_perm:[2,3,0,1] row_mask:0xf bank_mask:0xf
	s_nop 1
	v_add_f32_dpp v8, v8, v8 row_half_mirror row_mask:0xf bank_mask:0xf
	s_nop 1
	v_add_f32_dpp v8, v8, v8 row_mirror row_mask:0xf bank_mask:0xf
	s_nop 1
	v_readlane_b32 s14, v8, 0
	v_readlane_b32 s15, v8, 16
	v_readlane_b32 s24, v8, 32
	v_readlane_b32 s25, v8, 48
	s_nop 2
	v_mov_b32_e32 v19, s15
	v_mov_b32_e32 v29, s25
	v_add_f32_e32 v19, s14, v19
	v_add_f32_e32 v29, s24, v29
	v_add_f32_e32 v8, v19, v29
	v_fmamk_f32 v8, v8, 0x3b800000, v191
	v_mul_f32_e32 v19, 0x4f800000, v8
	v_cmp_gt_f32_e32 vcc, s76, v8
	s_nop 1
	v_cndmask_b32_e32 v8, v8, v19, vcc
	v_sqrt_f32_e32 v19, v8
	s_nop 0
	v_add_u32_e32 v29, -1, v19
	v_add_u32_e32 v34, 1, v19
	v_fma_f32 v35, -v29, v19, v8
	v_fma_f32 v36, -v34, v19, v8
	v_cmp_ge_f32_e64 s[14:15], 0, v35
	s_nop 1
	v_cndmask_b32_e64 v19, v19, v29, s[14:15]
	v_cmp_lt_f32_e64 s[14:15], 0, v36
	s_nop 1
	v_cndmask_b32_e64 v19, v19, v34, s[14:15]
	v_mul_f32_e32 v29, 0x37800000, v19
	v_cndmask_b32_e32 v19, v19, v29, vcc
	v_cmp_class_f32_e32 vcc, v8, v192
	s_nop 1
	v_cndmask_b32_e32 v8, v19, v8, vcc
	v_div_scale_f32 v19, s[14:15], v8, v8, 1.0
	v_rcp_f32_e32 v34, v19
	v_div_scale_f32 v29, vcc, 1.0, v8, 1.0
	v_fma_f32 v35, -v19, v34, 1.0
	v_fmac_f32_e32 v34, v35, v34
	v_mul_f32_e32 v35, v29, v34
	v_fma_f32 v36, -v19, v35, v29
	v_fmac_f32_e32 v35, v36, v34
	v_fma_f32 v19, -v19, v35, v29
	v_div_fmas_f32 v19, v19, v34, v35
	v_div_fixup_f32 v8, v19, v8, 1.0
	v_mul_f32_e32 v20, v20, v8
	v_mul_f32_e32 v21, v21, v8
	v_mul_f32_e32 v30, v30, v8
	v_mul_f32_e32 v31, v31, v8
	v_mul_f32_e32 v20, v4, v20
	v_mul_f32_e32 v21, v5, v21
	v_mul_f32_e32 v30, v2, v30
	v_mul_f32_e32 v31, v3, v31
	v_cvt_pk_bf16_f32 v32, v20, v21
	v_cvt_pk_bf16_f32 v33, v30, v31
	s_add_u32 s14, s52, 0xa000
	s_addc_u32 s15, s53, 0
	global_store_dwordx2 v184, v[32:33], s[14:15]
	v_lshlrev_b32_e32 v8, 16, v64
	v_lshlrev_b32_e32 v19, 16, v66
	v_and_b32_e32 v29, 0xffff0000, v64
	v_and_b32_e32 v34, 0xffff0000, v66
	v_fma_f32 v20, -v18, v19, v8
	v_fma_f32 v21, -v18, v34, v29
	v_lshlrev_b32_e32 v8, 16, v65
	v_lshlrev_b32_e32 v19, 16, v67
	v_and_b32_e32 v29, 0xffff0000, v65
	v_and_b32_e32 v34, 0xffff0000, v67
	v_fma_f32 v30, -v18, v19, v8
	v_fma_f32 v31, -v18, v34, v29
	v_mul_f32_e32 v8, v21, v21
	v_mul_f32_e32 v19, v31, v31
	v_fmac_f32_e32 v8, v20, v20
	v_fmac_f32_e32 v19, v30, v30
	v_add_f32_e32 v8, v8, v19
	s_nop 1
	v_add_f32_dpp v8, v8, v8 quad_perm:[1,0,3,2] row_mask:0xf bank_mask:0xf
	s_nop 1
	v_add_f32_dpp v8, v8, v8 quad_perm:[2,3,0,1] row_mask:0xf bank_mask:0xf
	s_nop 1
	v_add_f32_dpp v8, v8, v8 row_half_mirror row_mask:0xf bank_mask:0xf
	s_nop 1
	v_add_f32_dpp v8, v8, v8 row_mirror row_mask:0xf bank_mask:0xf
	s_nop 1
	v_readlane_b32 s14, v8, 0
	v_readlane_b32 s15, v8, 16
	v_readlane_b32 s24, v8, 32
	v_readlane_b32 s25, v8, 48
	s_nop 2
	v_mov_b32_e32 v19, s15
	v_mov_b32_e32 v29, s25
	v_add_f32_e32 v19, s14, v19
	v_add_f32_e32 v29, s24, v29
	v_add_f32_e32 v8, v19, v29
	v_fmamk_f32 v8, v8, 0x3b800000, v191
	v_mul_f32_e32 v19, 0x4f800000, v8
	v_cmp_gt_f32_e32 vcc, s76, v8
	s_nop 1
	v_cndmask_b32_e32 v8, v8, v19, vcc
	v_sqrt_f32_e32 v19, v8
	s_nop 0
	v_add_u32_e32 v29, -1, v19
	v_add_u32_e32 v34, 1, v19
	v_fma_f32 v35, -v29, v19, v8
	v_fma_f32 v36, -v34, v19, v8
	v_cmp_ge_f32_e64 s[14:15], 0, v35
	s_nop 1
	v_cndmask_b32_e64 v19, v19, v29, s[14:15]
	v_cmp_lt_f32_e64 s[14:15], 0, v36
	s_nop 1
	v_cndmask_b32_e64 v19, v19, v34, s[14:15]
	v_mul_f32_e32 v29, 0x37800000, v19
	v_cndmask_b32_e32 v19, v19, v29, vcc
	v_cmp_class_f32_e32 vcc, v8, v192
	s_nop 1
	v_cndmask_b32_e32 v8, v19, v8, vcc
	v_div_scale_f32 v19, s[14:15], v8, v8, 1.0
	v_rcp_f32_e32 v34, v19
	v_div_scale_f32 v29, vcc, 1.0, v8, 1.0
	v_fma_f32 v35, -v19, v34, 1.0
	v_fmac_f32_e32 v34, v35, v34
	v_mul_f32_e32 v35, v29, v34
	v_fma_f32 v36, -v19, v35, v29
	v_fmac_f32_e32 v35, v36, v34
	v_fma_f32 v19, -v19, v35, v29
	v_div_fmas_f32 v19, v19, v34, v35
	v_div_fixup_f32 v8, v19, v8, 1.0
	v_mul_f32_e32 v20, v20, v8
	v_mul_f32_e32 v21, v21, v8
	v_mul_f32_e32 v30, v30, v8
	v_mul_f32_e32 v31, v31, v8
	v_mul_f32_e32 v20, v4, v20
	v_mul_f32_e32 v21, v5, v21
	v_mul_f32_e32 v30, v2, v30
	v_mul_f32_e32 v31, v3, v31
	v_cvt_pk_bf16_f32 v32, v20, v21
	v_cvt_pk_bf16_f32 v33, v30, v31
	s_add_i32 s14, s50, 6
	s_and_b32 s14, s14, 0xfe
	s_or_b32 s14, s14, s48
	s_mov_b32 s15, s49
	s_lshl_b64 s[14:15], s[14:15], 13
	v_lshl_add_u64 v[10:11], v[0:1], 0, s[14:15]
	global_store_dwordx2 v[10:11], v[32:33], off
	v_lshlrev_b32_e32 v8, 16, v68
	v_lshlrev_b32_e32 v19, 16, v70
	v_and_b32_e32 v29, 0xffff0000, v68
	v_and_b32_e32 v34, 0xffff0000, v70
	v_fma_f32 v20, -v18, v19, v8
	v_fma_f32 v21, -v18, v34, v29
	v_lshlrev_b32_e32 v8, 16, v69
	v_lshlrev_b32_e32 v19, 16, v71
	v_and_b32_e32 v29, 0xffff0000, v69
	v_and_b32_e32 v34, 0xffff0000, v71
	v_fma_f32 v30, -v18, v19, v8
	v_fma_f32 v31, -v18, v34, v29
	v_mul_f32_e32 v8, v21, v21
	v_mul_f32_e32 v19, v31, v31
	v_fmac_f32_e32 v8, v20, v20
	v_fmac_f32_e32 v19, v30, v30
	v_add_f32_e32 v8, v8, v19
	s_nop 1
	v_add_f32_dpp v8, v8, v8 quad_perm:[1,0,3,2] row_mask:0xf bank_mask:0xf
	s_nop 1
	v_add_f32_dpp v8, v8, v8 quad_perm:[2,3,0,1] row_mask:0xf bank_mask:0xf
	s_nop 1
	v_add_f32_dpp v8, v8, v8 row_half_mirror row_mask:0xf bank_mask:0xf
	s_nop 1
	v_add_f32_dpp v8, v8, v8 row_mirror row_mask:0xf bank_mask:0xf
	s_nop 1
	v_readlane_b32 s14, v8, 0
	v_readlane_b32 s15, v8, 16
	v_readlane_b32 s24, v8, 32
	v_readlane_b32 s25, v8, 48
	s_nop 2
	v_mov_b32_e32 v19, s15
	v_mov_b32_e32 v29, s25
	v_add_f32_e32 v19, s14, v19
	v_add_f32_e32 v29, s24, v29
	v_add_f32_e32 v8, v19, v29
	v_fmamk_f32 v8, v8, 0x3b800000, v191
	v_mul_f32_e32 v19, 0x4f800000, v8
	v_cmp_gt_f32_e32 vcc, s76, v8
	s_nop 1
	v_cndmask_b32_e32 v8, v8, v19, vcc
	v_sqrt_f32_e32 v19, v8
	s_nop 0
	v_add_u32_e32 v29, -1, v19
	v_add_u32_e32 v34, 1, v19
	v_fma_f32 v35, -v29, v19, v8
	v_fma_f32 v36, -v34, v19, v8
	v_cmp_ge_f32_e64 s[14:15], 0, v35
	s_nop 1
	v_cndmask_b32_e64 v19, v19, v29, s[14:15]
	v_cmp_lt_f32_e64 s[14:15], 0, v36
	s_nop 1
	v_cndmask_b32_e64 v19, v19, v34, s[14:15]
	v_mul_f32_e32 v29, 0x37800000, v19
	v_cndmask_b32_e32 v19, v19, v29, vcc
	v_cmp_class_f32_e32 vcc, v8, v192
	s_nop 1
	v_cndmask_b32_e32 v8, v19, v8, vcc
	v_div_scale_f32 v19, s[14:15], v8, v8, 1.0
	v_rcp_f32_e32 v34, v19
	v_div_scale_f32 v29, vcc, 1.0, v8, 1.0
	v_fma_f32 v35, -v19, v34, 1.0
	v_fmac_f32_e32 v34, v35, v34
	v_mul_f32_e32 v35, v29, v34
	v_fma_f32 v36, -v19, v35, v29
	v_fmac_f32_e32 v35, v36, v34
	v_fma_f32 v19, -v19, v35, v29
	v_div_fmas_f32 v19, v19, v34, v35
	v_div_fixup_f32 v8, v19, v8, 1.0
	v_mul_f32_e32 v20, v20, v8
	v_mul_f32_e32 v21, v21, v8
	v_mul_f32_e32 v30, v30, v8
	v_mul_f32_e32 v31, v31, v8
	v_mul_f32_e32 v20, v4, v20
	v_mul_f32_e32 v21, v5, v21
	v_mul_f32_e32 v30, v2, v30
	v_mul_f32_e32 v31, v3, v31
	v_cvt_pk_bf16_f32 v32, v20, v21
	v_cvt_pk_bf16_f32 v33, v30, v31
	s_add_u32 s14, s52, 0xe000
	s_addc_u32 s15, s53, 0
	global_store_dwordx2 v184, v[32:33], s[14:15]
	s_add_u32 s4, s96, 0xd000
	s_addc_u32 s5, s97, 0
	s_add_u32 s6, s98, 0xd000
	s_addc_u32 s7, s99, 0
	global_load_dwordx2 v[56:57], v184, s[4:5] offset:-4096
	global_load_dwordx2 v[58:59], v184, s[6:7] offset:-4096
	global_load_dwordx2 v[60:61], v184, s[4:5]
	global_load_dwordx2 v[62:63], v184, s[6:7]
	s_add_u32 s4, s4, 0x2000
	s_addc_u32 s5, s5, 0
	s_add_u32 s6, s6, 0x2000
	s_addc_u32 s7, s7, 0
	global_load_dwordx2 v[64:65], v184, s[4:5] offset:-4096
	global_load_dwordx2 v[66:67], v184, s[6:7] offset:-4096
	global_load_dwordx2 v[68:69], v184, s[4:5]
	global_load_dwordx2 v[70:71], v184, s[6:7]
	s_waitcnt vmcnt(12)
	v_lshlrev_b32_e32 v8, 16, v40
	v_lshlrev_b32_e32 v19, 16, v42
	v_and_b32_e32 v29, 0xffff0000, v40
	v_and_b32_e32 v34, 0xffff0000, v42
	v_fma_f32 v20, -v18, v19, v8
	v_fma_f32 v21, -v18, v34, v29
	v_lshlrev_b32_e32 v8, 16, v41
	v_lshlrev_b32_e32 v19, 16, v43
	v_and_b32_e32 v29, 0xffff0000, v41
	v_and_b32_e32 v34, 0xffff0000, v43
	v_fma_f32 v30, -v18, v19, v8
	v_fma_f32 v31, -v18, v34, v29
	v_mul_f32_e32 v8, v21, v21
	v_mul_f32_e32 v19, v31, v31
	v_fmac_f32_e32 v8, v20, v20
	v_fmac_f32_e32 v19, v30, v30
	v_add_f32_e32 v8, v8, v19
	s_nop 1
	v_add_f32_dpp v8, v8, v8 quad_perm:[1,0,3,2] row_mask:0xf bank_mask:0xf
	s_nop 1
	v_add_f32_dpp v8, v8, v8 quad_perm:[2,3,0,1] row_mask:0xf bank_mask:0xf
	s_nop 1
	v_add_f32_dpp v8, v8, v8 row_half_mirror row_mask:0xf bank_mask:0xf
	s_nop 1
	v_add_f32_dpp v8, v8, v8 row_mirror row_mask:0xf bank_mask:0xf
	s_nop 1
	v_readlane_b32 s14, v8, 0
	v_readlane_b32 s15, v8, 16
	v_readlane_b32 s24, v8, 32
	v_readlane_b32 s25, v8, 48
	s_nop 2
	v_mov_b32_e32 v19, s15
	v_mov_b32_e32 v29, s25
	v_add_f32_e32 v19, s14, v19
	v_add_f32_e32 v29, s24, v29
	v_add_f32_e32 v8, v19, v29
	v_fmamk_f32 v8, v8, 0x3b800000, v191
	v_mul_f32_e32 v19, 0x4f800000, v8
	v_cmp_gt_f32_e32 vcc, s76, v8
	s_nop 1
	v_cndmask_b32_e32 v8, v8, v19, vcc
	v_sqrt_f32_e32 v19, v8
	s_nop 0
	v_add_u32_e32 v29, -1, v19
	v_add_u32_e32 v34, 1, v19
	v_fma_f32 v35, -v29, v19, v8
	v_fma_f32 v36, -v34, v19, v8
	v_cmp_ge_f32_e64 s[14:15], 0, v35
	s_nop 1
	v_cndmask_b32_e64 v19, v19, v29, s[14:15]
	v_cmp_lt_f32_e64 s[14:15], 0, v36
	s_nop 1
	v_cndmask_b32_e64 v19, v19, v34, s[14:15]
	v_mul_f32_e32 v29, 0x37800000, v19
	v_cndmask_b32_e32 v19, v19, v29, vcc
	v_cmp_class_f32_e32 vcc, v8, v192
	s_nop 1
	v_cndmask_b32_e32 v8, v19, v8, vcc
	v_div_scale_f32 v19, s[14:15], v8, v8, 1.0
	v_rcp_f32_e32 v34, v19
	v_div_scale_f32 v29, vcc, 1.0, v8, 1.0
	v_fma_f32 v35, -v19, v34, 1.0
	v_fmac_f32_e32 v34, v35, v34
	v_mul_f32_e32 v35, v29, v34
	v_fma_f32 v36, -v19, v35, v29
	v_fmac_f32_e32 v35, v36, v34
	v_fma_f32 v19, -v19, v35, v29
	v_div_fmas_f32 v19, v19, v34, v35
	v_div_fixup_f32 v8, v19, v8, 1.0
	v_mul_f32_e32 v20, v20, v8
	v_mul_f32_e32 v21, v21, v8
	v_mul_f32_e32 v30, v30, v8
	v_mul_f32_e32 v31, v31, v8
	v_mul_f32_e32 v20, v4, v20
	v_mul_f32_e32 v21, v5, v21
	v_mul_f32_e32 v30, v2, v30
	v_mul_f32_e32 v31, v3, v31
	v_cvt_pk_bf16_f32 v32, v20, v21
	v_cvt_pk_bf16_f32 v33, v30, v31
	s_add_i32 s14, s50, 8
	s_and_b32 s14, s14, 0xfc
	s_or_b32 s14, s14, s48
	s_mov_b32 s15, s49
	s_lshl_b64 s[14:15], s[14:15], 13
	v_lshl_add_u64 v[10:11], v[0:1], 0, s[14:15]
	global_store_dwordx2 v[10:11], v[32:33], off
	v_lshlrev_b32_e32 v8, 16, v44
	v_lshlrev_b32_e32 v19, 16, v46
	v_and_b32_e32 v29, 0xffff0000, v44
	v_and_b32_e32 v34, 0xffff0000, v46
	v_fma_f32 v20, -v18, v19, v8
	v_fma_f32 v21, -v18, v34, v29
	v_lshlrev_b32_e32 v8, 16, v45
	v_lshlrev_b32_e32 v19, 16, v47
	v_and_b32_e32 v29, 0xffff0000, v45
	v_and_b32_e32 v34, 0xffff0000, v47
	v_fma_f32 v30, -v18, v19, v8
	v_fma_f32 v31, -v18, v34, v29
	v_mul_f32_e32 v8, v21, v21
	v_mul_f32_e32 v19, v31, v31
	v_fmac_f32_e32 v8, v20, v20
	v_fmac_f32_e32 v19, v30, v30
	v_add_f32_e32 v8, v8, v19
	s_nop 1
	v_add_f32_dpp v8, v8, v8 quad_perm:[1,0,3,2] row_mask:0xf bank_mask:0xf
	s_nop 1
	v_add_f32_dpp v8, v8, v8 quad_perm:[2,3,0,1] row_mask:0xf bank_mask:0xf
	s_nop 1
	v_add_f32_dpp v8, v8, v8 row_half_mirror row_mask:0xf bank_mask:0xf
	s_nop 1
	v_add_f32_dpp v8, v8, v8 row_mirror row_mask:0xf bank_mask:0xf
	s_nop 1
	v_readlane_b32 s14, v8, 0
	v_readlane_b32 s15, v8, 16
	v_readlane_b32 s24, v8, 32
	v_readlane_b32 s25, v8, 48
	s_nop 2
	v_mov_b32_e32 v19, s15
	v_mov_b32_e32 v29, s25
	v_add_f32_e32 v19, s14, v19
	v_add_f32_e32 v29, s24, v29
	v_add_f32_e32 v8, v19, v29
	v_fmamk_f32 v8, v8, 0x3b800000, v191
	v_mul_f32_e32 v19, 0x4f800000, v8
	v_cmp_gt_f32_e32 vcc, s76, v8
	s_nop 1
	v_cndmask_b32_e32 v8, v8, v19, vcc
	v_sqrt_f32_e32 v19, v8
	s_nop 0
	v_add_u32_e32 v29, -1, v19
	v_add_u32_e32 v34, 1, v19
	v_fma_f32 v35, -v29, v19, v8
	v_fma_f32 v36, -v34, v19, v8
	v_cmp_ge_f32_e64 s[14:15], 0, v35
	s_nop 1
	v_cndmask_b32_e64 v19, v19, v29, s[14:15]
	v_cmp_lt_f32_e64 s[14:15], 0, v36
	s_nop 1
	v_cndmask_b32_e64 v19, v19, v34, s[14:15]
	v_mul_f32_e32 v29, 0x37800000, v19
	v_cndmask_b32_e32 v19, v19, v29, vcc
	v_cmp_class_f32_e32 vcc, v8, v192
	s_nop 1
	v_cndmask_b32_e32 v8, v19, v8, vcc
	v_div_scale_f32 v19, s[14:15], v8, v8, 1.0
	v_rcp_f32_e32 v34, v19
	v_div_scale_f32 v29, vcc, 1.0, v8, 1.0
	v_fma_f32 v35, -v19, v34, 1.0
	v_fmac_f32_e32 v34, v35, v34
	v_mul_f32_e32 v35, v29, v34
	v_fma_f32 v36, -v19, v35, v29
	v_fmac_f32_e32 v35, v36, v34
	v_fma_f32 v19, -v19, v35, v29
	v_div_fmas_f32 v19, v19, v34, v35
	v_div_fixup_f32 v8, v19, v8, 1.0
	v_mul_f32_e32 v20, v20, v8
	v_mul_f32_e32 v21, v21, v8
	v_mul_f32_e32 v30, v30, v8
	v_mul_f32_e32 v31, v31, v8
	v_mul_f32_e32 v20, v4, v20
	v_mul_f32_e32 v21, v5, v21
	v_mul_f32_e32 v30, v2, v30
	v_mul_f32_e32 v31, v3, v31
	v_cvt_pk_bf16_f32 v32, v20, v21
	v_cvt_pk_bf16_f32 v33, v30, v31
	s_add_u32 s14, s52, 0x12000
	s_addc_u32 s15, s53, 0
	global_store_dwordx2 v184, v[32:33], s[14:15]
	v_lshlrev_b32_e32 v8, 16, v48
	v_lshlrev_b32_e32 v19, 16, v50
	v_and_b32_e32 v29, 0xffff0000, v48
	v_and_b32_e32 v34, 0xffff0000, v50
	v_fma_f32 v20, -v18, v19, v8
	v_fma_f32 v21, -v18, v34, v29
	v_lshlrev_b32_e32 v8, 16, v49
	v_lshlrev_b32_e32 v19, 16, v51
	v_and_b32_e32 v29, 0xffff0000, v49
	v_and_b32_e32 v34, 0xffff0000, v51
	v_fma_f32 v30, -v18, v19, v8
	v_fma_f32 v31, -v18, v34, v29
	v_mul_f32_e32 v8, v21, v21
	v_mul_f32_e32 v19, v31, v31
	v_fmac_f32_e32 v8, v20, v20
	v_fmac_f32_e32 v19, v30, v30
	v_add_f32_e32 v8, v8, v19
	s_nop 1
	v_add_f32_dpp v8, v8, v8 quad_perm:[1,0,3,2] row_mask:0xf bank_mask:0xf
	s_nop 1
	v_add_f32_dpp v8, v8, v8 quad_perm:[2,3,0,1] row_mask:0xf bank_mask:0xf
	s_nop 1
	v_add_f32_dpp v8, v8, v8 row_half_mirror row_mask:0xf bank_mask:0xf
	s_nop 1
	v_add_f32_dpp v8, v8, v8 row_mirror row_mask:0xf bank_mask:0xf
	s_nop 1
	v_readlane_b32 s14, v8, 0
	v_readlane_b32 s15, v8, 16
	v_readlane_b32 s24, v8, 32
	v_readlane_b32 s25, v8, 48
	s_nop 2
	v_mov_b32_e32 v19, s15
	v_mov_b32_e32 v29, s25
	v_add_f32_e32 v19, s14, v19
	v_add_f32_e32 v29, s24, v29
	v_add_f32_e32 v8, v19, v29
	v_fmamk_f32 v8, v8, 0x3b800000, v191
	v_mul_f32_e32 v19, 0x4f800000, v8
	v_cmp_gt_f32_e32 vcc, s76, v8
	s_nop 1
	v_cndmask_b32_e32 v8, v8, v19, vcc
	v_sqrt_f32_e32 v19, v8
	s_nop 0
	v_add_u32_e32 v29, -1, v19
	v_add_u32_e32 v34, 1, v19
	v_fma_f32 v35, -v29, v19, v8
	v_fma_f32 v36, -v34, v19, v8
	v_cmp_ge_f32_e64 s[14:15], 0, v35
	s_nop 1
	v_cndmask_b32_e64 v19, v19, v29, s[14:15]
	v_cmp_lt_f32_e64 s[14:15], 0, v36
	s_nop 1
	v_cndmask_b32_e64 v19, v19, v34, s[14:15]
	v_mul_f32_e32 v29, 0x37800000, v19
	v_cndmask_b32_e32 v19, v19, v29, vcc
	v_cmp_class_f32_e32 vcc, v8, v192
	s_nop 1
	v_cndmask_b32_e32 v8, v19, v8, vcc
	v_div_scale_f32 v19, s[14:15], v8, v8, 1.0
	v_rcp_f32_e32 v34, v19
	v_div_scale_f32 v29, vcc, 1.0, v8, 1.0
	v_fma_f32 v35, -v19, v34, 1.0
	v_fmac_f32_e32 v34, v35, v34
	v_mul_f32_e32 v35, v29, v34
	v_fma_f32 v36, -v19, v35, v29
	v_fmac_f32_e32 v35, v36, v34
	v_fma_f32 v19, -v19, v35, v29
	v_div_fmas_f32 v19, v19, v34, v35
	v_div_fixup_f32 v8, v19, v8, 1.0
	v_mul_f32_e32 v20, v20, v8
	v_mul_f32_e32 v21, v21, v8
	v_mul_f32_e32 v30, v30, v8
	v_mul_f32_e32 v31, v31, v8
	v_mul_f32_e32 v20, v4, v20
	v_mul_f32_e32 v21, v5, v21
	v_mul_f32_e32 v30, v2, v30
	v_mul_f32_e32 v31, v3, v31
	v_cvt_pk_bf16_f32 v32, v20, v21
	v_cvt_pk_bf16_f32 v33, v30, v31
	s_add_i32 s14, s50, 10
	s_and_b32 s14, s14, 0xfe
	s_or_b32 s14, s14, s48
	s_mov_b32 s15, s49
	s_lshl_b64 s[14:15], s[14:15], 13
	v_lshl_add_u64 v[10:11], v[0:1], 0, s[14:15]
	global_store_dwordx2 v[10:11], v[32:33], off
	v_lshlrev_b32_e32 v8, 16, v52
	v_lshlrev_b32_e32 v19, 16, v54
	v_and_b32_e32 v29, 0xffff0000, v52
	v_and_b32_e32 v34, 0xffff0000, v54
	v_fma_f32 v20, -v18, v19, v8
	v_fma_f32 v21, -v18, v34, v29
	v_lshlrev_b32_e32 v8, 16, v53
	v_lshlrev_b32_e32 v19, 16, v55
	v_and_b32_e32 v29, 0xffff0000, v53
	v_and_b32_e32 v34, 0xffff0000, v55
	v_fma_f32 v30, -v18, v19, v8
	v_fma_f32 v31, -v18, v34, v29
	v_mul_f32_e32 v8, v21, v21
	v_mul_f32_e32 v19, v31, v31
	v_fmac_f32_e32 v8, v20, v20
	v_fmac_f32_e32 v19, v30, v30
	v_add_f32_e32 v8, v8, v19
	s_nop 1
	v_add_f32_dpp v8, v8, v8 quad_perm:[1,0,3,2] row_mask:0xf bank_mask:0xf
	s_nop 1
	v_add_f32_dpp v8, v8, v8 quad_perm:[2,3,0,1] row_mask:0xf bank_mask:0xf
	s_nop 1
	v_add_f32_dpp v8, v8, v8 row_half_mirror row_mask:0xf bank_mask:0xf
	s_nop 1
	v_add_f32_dpp v8, v8, v8 row_mirror row_mask:0xf bank_mask:0xf
	s_nop 1
	v_readlane_b32 s14, v8, 0
	v_readlane_b32 s15, v8, 16
	v_readlane_b32 s24, v8, 32
	v_readlane_b32 s25, v8, 48
	s_nop 2
	v_mov_b32_e32 v19, s15
	v_mov_b32_e32 v29, s25
	v_add_f32_e32 v19, s14, v19
	v_add_f32_e32 v29, s24, v29
	v_add_f32_e32 v8, v19, v29
	v_fmamk_f32 v8, v8, 0x3b800000, v191
	v_mul_f32_e32 v19, 0x4f800000, v8
	v_cmp_gt_f32_e32 vcc, s76, v8
	s_nop 1
	v_cndmask_b32_e32 v8, v8, v19, vcc
	v_sqrt_f32_e32 v19, v8
	s_nop 0
	v_add_u32_e32 v29, -1, v19
	v_add_u32_e32 v34, 1, v19
	v_fma_f32 v35, -v29, v19, v8
	v_fma_f32 v36, -v34, v19, v8
	v_cmp_ge_f32_e64 s[14:15], 0, v35
	s_nop 1
	v_cndmask_b32_e64 v19, v19, v29, s[14:15]
	v_cmp_lt_f32_e64 s[14:15], 0, v36
	s_nop 1
	v_cndmask_b32_e64 v19, v19, v34, s[14:15]
	v_mul_f32_e32 v29, 0x37800000, v19
	v_cndmask_b32_e32 v19, v19, v29, vcc
	v_cmp_class_f32_e32 vcc, v8, v192
	s_nop 1
	v_cndmask_b32_e32 v8, v19, v8, vcc
	v_div_scale_f32 v19, s[14:15], v8, v8, 1.0
	v_rcp_f32_e32 v34, v19
	v_div_scale_f32 v29, vcc, 1.0, v8, 1.0
	v_fma_f32 v35, -v19, v34, 1.0
	v_fmac_f32_e32 v34, v35, v34
	v_mul_f32_e32 v35, v29, v34
	v_fma_f32 v36, -v19, v35, v29
	v_fmac_f32_e32 v35, v36, v34
	v_fma_f32 v19, -v19, v35, v29
	v_div_fmas_f32 v19, v19, v34, v35
	v_div_fixup_f32 v8, v19, v8, 1.0
	v_mul_f32_e32 v20, v20, v8
	v_mul_f32_e32 v21, v21, v8
	v_mul_f32_e32 v30, v30, v8
	v_mul_f32_e32 v31, v31, v8
	v_mul_f32_e32 v20, v4, v20
	v_mul_f32_e32 v21, v5, v21
	v_mul_f32_e32 v30, v2, v30
	v_mul_f32_e32 v31, v3, v31
	v_cvt_pk_bf16_f32 v32, v20, v21
	v_cvt_pk_bf16_f32 v33, v30, v31
	s_add_u32 s14, s52, 0x16000
	s_addc_u32 s15, s53, 0
	global_store_dwordx2 v184, v[32:33], s[14:15]
	s_add_u32 s4, s96, 0x11000
	s_addc_u32 s5, s97, 0
	s_add_u32 s6, s98, 0x11000
	s_addc_u32 s7, s99, 0
	global_load_dwordx2 v[40:41], v184, s[4:5] offset:-4096
	global_load_dwordx2 v[42:43], v184, s[6:7] offset:-4096
	global_load_dwordx2 v[44:45], v184, s[4:5]
	global_load_dwordx2 v[46:47], v184, s[6:7]
	s_add_u32 s4, s4, 0x2000
	s_addc_u32 s5, s5, 0
	s_add_u32 s6, s6, 0x2000
	s_addc_u32 s7, s7, 0
	global_load_dwordx2 v[48:49], v184, s[4:5] offset:-4096
	global_load_dwordx2 v[50:51], v184, s[6:7] offset:-4096
	global_load_dwordx2 v[52:53], v184, s[4:5]
	global_load_dwordx2 v[54:55], v184, s[6:7]
	s_waitcnt vmcnt(12)
	v_lshlrev_b32_e32 v8, 16, v56
	v_lshlrev_b32_e32 v19, 16, v58
	v_and_b32_e32 v29, 0xffff0000, v56
	v_and_b32_e32 v34, 0xffff0000, v58
	v_fma_f32 v20, -v18, v19, v8
	v_fma_f32 v21, -v18, v34, v29
	v_lshlrev_b32_e32 v8, 16, v57
	v_lshlrev_b32_e32 v19, 16, v59
	v_and_b32_e32 v29, 0xffff0000, v57
	v_and_b32_e32 v34, 0xffff0000, v59
	v_fma_f32 v30, -v18, v19, v8
	v_fma_f32 v31, -v18, v34, v29
	v_mul_f32_e32 v8, v21, v21
	v_mul_f32_e32 v19, v31, v31
	v_fmac_f32_e32 v8, v20, v20
	v_fmac_f32_e32 v19, v30, v30
	v_add_f32_e32 v8, v8, v19
	s_nop 1
	v_add_f32_dpp v8, v8, v8 quad_perm:[1,0,3,2] row_mask:0xf bank_mask:0xf
	s_nop 1
	v_add_f32_dpp v8, v8, v8 quad_perm:[2,3,0,1] row_mask:0xf bank_mask:0xf
	s_nop 1
	v_add_f32_dpp v8, v8, v8 row_half_mirror row_mask:0xf bank_mask:0xf
	s_nop 1
	v_add_f32_dpp v8, v8, v8 row_mirror row_mask:0xf bank_mask:0xf
	s_nop 1
	v_readlane_b32 s14, v8, 0
	v_readlane_b32 s15, v8, 16
	v_readlane_b32 s24, v8, 32
	v_readlane_b32 s25, v8, 48
	s_nop 2
	v_mov_b32_e32 v19, s15
	v_mov_b32_e32 v29, s25
	v_add_f32_e32 v19, s14, v19
	v_add_f32_e32 v29, s24, v29
	v_add_f32_e32 v8, v19, v29
	v_fmamk_f32 v8, v8, 0x3b800000, v191
	v_mul_f32_e32 v19, 0x4f800000, v8
	v_cmp_gt_f32_e32 vcc, s76, v8
	s_nop 1
	v_cndmask_b32_e32 v8, v8, v19, vcc
	v_sqrt_f32_e32 v19, v8
	s_nop 0
	v_add_u32_e32 v29, -1, v19
	v_add_u32_e32 v34, 1, v19
	v_fma_f32 v35, -v29, v19, v8
	v_fma_f32 v36, -v34, v19, v8
	v_cmp_ge_f32_e64 s[14:15], 0, v35
	s_nop 1
	v_cndmask_b32_e64 v19, v19, v29, s[14:15]
	v_cmp_lt_f32_e64 s[14:15], 0, v36
	s_nop 1
	v_cndmask_b32_e64 v19, v19, v34, s[14:15]
	v_mul_f32_e32 v29, 0x37800000, v19
	v_cndmask_b32_e32 v19, v19, v29, vcc
	v_cmp_class_f32_e32 vcc, v8, v192
	s_nop 1
	v_cndmask_b32_e32 v8, v19, v8, vcc
	v_div_scale_f32 v19, s[14:15], v8, v8, 1.0
	v_rcp_f32_e32 v34, v19
	v_div_scale_f32 v29, vcc, 1.0, v8, 1.0
	v_fma_f32 v35, -v19, v34, 1.0
	v_fmac_f32_e32 v34, v35, v34
	v_mul_f32_e32 v35, v29, v34
	v_fma_f32 v36, -v19, v35, v29
	v_fmac_f32_e32 v35, v36, v34
	v_fma_f32 v19, -v19, v35, v29
	v_div_fmas_f32 v19, v19, v34, v35
	v_div_fixup_f32 v8, v19, v8, 1.0
	v_mul_f32_e32 v20, v20, v8
	v_mul_f32_e32 v21, v21, v8
	v_mul_f32_e32 v30, v30, v8
	v_mul_f32_e32 v31, v31, v8
	v_mul_f32_e32 v20, v4, v20
	v_mul_f32_e32 v21, v5, v21
	v_mul_f32_e32 v30, v2, v30
	v_mul_f32_e32 v31, v3, v31
	v_cvt_pk_bf16_f32 v32, v20, v21
	v_cvt_pk_bf16_f32 v33, v30, v31
	s_add_i32 s14, s50, 12
	s_and_b32 s14, s14, 0xfc
	s_or_b32 s14, s14, s48
	s_mov_b32 s15, s49
	s_lshl_b64 s[14:15], s[14:15], 13
	v_lshl_add_u64 v[10:11], v[0:1], 0, s[14:15]
	global_store_dwordx2 v[10:11], v[32:33], off
	v_lshlrev_b32_e32 v8, 16, v60
	v_lshlrev_b32_e32 v19, 16, v62
	v_and_b32_e32 v29, 0xffff0000, v60
	v_and_b32_e32 v34, 0xffff0000, v62
	v_fma_f32 v20, -v18, v19, v8
	v_fma_f32 v21, -v18, v34, v29
	v_lshlrev_b32_e32 v8, 16, v61
	v_lshlrev_b32_e32 v19, 16, v63
	v_and_b32_e32 v29, 0xffff0000, v61
	v_and_b32_e32 v34, 0xffff0000, v63
	v_fma_f32 v30, -v18, v19, v8
	v_fma_f32 v31, -v18, v34, v29
	v_mul_f32_e32 v8, v21, v21
	v_mul_f32_e32 v19, v31, v31
	v_fmac_f32_e32 v8, v20, v20
	v_fmac_f32_e32 v19, v30, v30
	v_add_f32_e32 v8, v8, v19
	s_nop 1
	v_add_f32_dpp v8, v8, v8 quad_perm:[1,0,3,2] row_mask:0xf bank_mask:0xf
	s_nop 1
	v_add_f32_dpp v8, v8, v8 quad_perm:[2,3,0,1] row_mask:0xf bank_mask:0xf
	s_nop 1
	v_add_f32_dpp v8, v8, v8 row_half_mirror row_mask:0xf bank_mask:0xf
	s_nop 1
	v_add_f32_dpp v8, v8, v8 row_mirror row_mask:0xf bank_mask:0xf
	s_nop 1
	v_readlane_b32 s14, v8, 0
	v_readlane_b32 s15, v8, 16
	v_readlane_b32 s24, v8, 32
	v_readlane_b32 s25, v8, 48
	s_nop 2
	v_mov_b32_e32 v19, s15
	v_mov_b32_e32 v29, s25
	v_add_f32_e32 v19, s14, v19
	v_add_f32_e32 v29, s24, v29
	v_add_f32_e32 v8, v19, v29
	v_fmamk_f32 v8, v8, 0x3b800000, v191
	v_mul_f32_e32 v19, 0x4f800000, v8
	v_cmp_gt_f32_e32 vcc, s76, v8
	s_nop 1
	v_cndmask_b32_e32 v8, v8, v19, vcc
	v_sqrt_f32_e32 v19, v8
	s_nop 0
	v_add_u32_e32 v29, -1, v19
	v_add_u32_e32 v34, 1, v19
	v_fma_f32 v35, -v29, v19, v8
	v_fma_f32 v36, -v34, v19, v8
	v_cmp_ge_f32_e64 s[14:15], 0, v35
	s_nop 1
	v_cndmask_b32_e64 v19, v19, v29, s[14:15]
	v_cmp_lt_f32_e64 s[14:15], 0, v36
	s_nop 1
	v_cndmask_b32_e64 v19, v19, v34, s[14:15]
	v_mul_f32_e32 v29, 0x37800000, v19
	v_cndmask_b32_e32 v19, v19, v29, vcc
	v_cmp_class_f32_e32 vcc, v8, v192
	s_nop 1
	v_cndmask_b32_e32 v8, v19, v8, vcc
	v_div_scale_f32 v19, s[14:15], v8, v8, 1.0
	v_rcp_f32_e32 v34, v19
	v_div_scale_f32 v29, vcc, 1.0, v8, 1.0
	v_fma_f32 v35, -v19, v34, 1.0
	v_fmac_f32_e32 v34, v35, v34
	v_mul_f32_e32 v35, v29, v34
	v_fma_f32 v36, -v19, v35, v29
	v_fmac_f32_e32 v35, v36, v34
	v_fma_f32 v19, -v19, v35, v29
	v_div_fmas_f32 v19, v19, v34, v35
	v_div_fixup_f32 v8, v19, v8, 1.0
	v_mul_f32_e32 v20, v20, v8
	v_mul_f32_e32 v21, v21, v8
	v_mul_f32_e32 v30, v30, v8
	v_mul_f32_e32 v31, v31, v8
	v_mul_f32_e32 v20, v4, v20
	v_mul_f32_e32 v21, v5, v21
	v_mul_f32_e32 v30, v2, v30
	v_mul_f32_e32 v31, v3, v31
	v_cvt_pk_bf16_f32 v32, v20, v21
	v_cvt_pk_bf16_f32 v33, v30, v31
	s_add_u32 s14, s52, 0x1a000
	s_addc_u32 s15, s53, 0
	global_store_dwordx2 v184, v[32:33], s[14:15]
	v_lshlrev_b32_e32 v8, 16, v64
	v_lshlrev_b32_e32 v19, 16, v66
	v_and_b32_e32 v29, 0xffff0000, v64
	v_and_b32_e32 v34, 0xffff0000, v66
	v_fma_f32 v20, -v18, v19, v8
	v_fma_f32 v21, -v18, v34, v29
	v_lshlrev_b32_e32 v8, 16, v65
	v_lshlrev_b32_e32 v19, 16, v67
	v_and_b32_e32 v29, 0xffff0000, v65
	v_and_b32_e32 v34, 0xffff0000, v67
	v_fma_f32 v30, -v18, v19, v8
	v_fma_f32 v31, -v18, v34, v29
	v_mul_f32_e32 v8, v21, v21
	v_mul_f32_e32 v19, v31, v31
	v_fmac_f32_e32 v8, v20, v20
	v_fmac_f32_e32 v19, v30, v30
	v_add_f32_e32 v8, v8, v19
	s_nop 1
	v_add_f32_dpp v8, v8, v8 quad_perm:[1,0,3,2] row_mask:0xf bank_mask:0xf
	s_nop 1
	v_add_f32_dpp v8, v8, v8 quad_perm:[2,3,0,1] row_mask:0xf bank_mask:0xf
	s_nop 1
	v_add_f32_dpp v8, v8, v8 row_half_mirror row_mask:0xf bank_mask:0xf
	s_nop 1
	v_add_f32_dpp v8, v8, v8 row_mirror row_mask:0xf bank_mask:0xf
	s_nop 1
	v_readlane_b32 s14, v8, 0
	v_readlane_b32 s15, v8, 16
	v_readlane_b32 s24, v8, 32
	v_readlane_b32 s25, v8, 48
	s_nop 2
	v_mov_b32_e32 v19, s15
	v_mov_b32_e32 v29, s25
	v_add_f32_e32 v19, s14, v19
	v_add_f32_e32 v29, s24, v29
	v_add_f32_e32 v8, v19, v29
	v_fmamk_f32 v8, v8, 0x3b800000, v191
	v_mul_f32_e32 v19, 0x4f800000, v8
	v_cmp_gt_f32_e32 vcc, s76, v8
	s_nop 1
	v_cndmask_b32_e32 v8, v8, v19, vcc
	v_sqrt_f32_e32 v19, v8
	s_nop 0
	v_add_u32_e32 v29, -1, v19
	v_add_u32_e32 v34, 1, v19
	v_fma_f32 v35, -v29, v19, v8
	v_fma_f32 v36, -v34, v19, v8
	v_cmp_ge_f32_e64 s[14:15], 0, v35
	s_nop 1
	v_cndmask_b32_e64 v19, v19, v29, s[14:15]
	v_cmp_lt_f32_e64 s[14:15], 0, v36
	s_nop 1
	v_cndmask_b32_e64 v19, v19, v34, s[14:15]
	v_mul_f32_e32 v29, 0x37800000, v19
	v_cndmask_b32_e32 v19, v19, v29, vcc
	v_cmp_class_f32_e32 vcc, v8, v192
	s_nop 1
	v_cndmask_b32_e32 v8, v19, v8, vcc
	v_div_scale_f32 v19, s[14:15], v8, v8, 1.0
	v_rcp_f32_e32 v34, v19
	v_div_scale_f32 v29, vcc, 1.0, v8, 1.0
	v_fma_f32 v35, -v19, v34, 1.0
	v_fmac_f32_e32 v34, v35, v34
	v_mul_f32_e32 v35, v29, v34
	v_fma_f32 v36, -v19, v35, v29
	v_fmac_f32_e32 v35, v36, v34
	v_fma_f32 v19, -v19, v35, v29
	v_div_fmas_f32 v19, v19, v34, v35
	v_div_fixup_f32 v8, v19, v8, 1.0
	v_mul_f32_e32 v20, v20, v8
	v_mul_f32_e32 v21, v21, v8
	v_mul_f32_e32 v30, v30, v8
	v_mul_f32_e32 v31, v31, v8
	v_mul_f32_e32 v20, v4, v20
	v_mul_f32_e32 v21, v5, v21
	v_mul_f32_e32 v30, v2, v30
	v_mul_f32_e32 v31, v3, v31
	v_cvt_pk_bf16_f32 v32, v20, v21
	v_cvt_pk_bf16_f32 v33, v30, v31
	s_add_i32 s14, s50, 14
	s_and_b32 s14, s14, 0xfe
	s_or_b32 s14, s14, s48
	s_mov_b32 s15, s49
	s_lshl_b64 s[14:15], s[14:15], 13
	v_lshl_add_u64 v[10:11], v[0:1], 0, s[14:15]
	global_store_dwordx2 v[10:11], v[32:33], off
	v_lshlrev_b32_e32 v8, 16, v68
	v_lshlrev_b32_e32 v19, 16, v70
	v_and_b32_e32 v29, 0xffff0000, v68
	v_and_b32_e32 v34, 0xffff0000, v70
	v_fma_f32 v20, -v18, v19, v8
	v_fma_f32 v21, -v18, v34, v29
	v_lshlrev_b32_e32 v8, 16, v69
	v_lshlrev_b32_e32 v19, 16, v71
	v_and_b32_e32 v29, 0xffff0000, v69
	v_and_b32_e32 v34, 0xffff0000, v71
	v_fma_f32 v30, -v18, v19, v8
	v_fma_f32 v31, -v18, v34, v29
	v_mul_f32_e32 v8, v21, v21
	v_mul_f32_e32 v19, v31, v31
	v_fmac_f32_e32 v8, v20, v20
	v_fmac_f32_e32 v19, v30, v30
	v_add_f32_e32 v8, v8, v19
	s_nop 1
	v_add_f32_dpp v8, v8, v8 quad_perm:[1,0,3,2] row_mask:0xf bank_mask:0xf
	s_nop 1
	v_add_f32_dpp v8, v8, v8 quad_perm:[2,3,0,1] row_mask:0xf bank_mask:0xf
	s_nop 1
	v_add_f32_dpp v8, v8, v8 row_half_mirror row_mask:0xf bank_mask:0xf
	s_nop 1
	v_add_f32_dpp v8, v8, v8 row_mirror row_mask:0xf bank_mask:0xf
	s_nop 1
	v_readlane_b32 s14, v8, 0
	v_readlane_b32 s15, v8, 16
	v_readlane_b32 s24, v8, 32
	v_readlane_b32 s25, v8, 48
	s_nop 2
	v_mov_b32_e32 v19, s15
	v_mov_b32_e32 v29, s25
	v_add_f32_e32 v19, s14, v19
	v_add_f32_e32 v29, s24, v29
	v_add_f32_e32 v8, v19, v29
	v_fmamk_f32 v8, v8, 0x3b800000, v191
	v_mul_f32_e32 v19, 0x4f800000, v8
	v_cmp_gt_f32_e32 vcc, s76, v8
	s_nop 1
	v_cndmask_b32_e32 v8, v8, v19, vcc
	v_sqrt_f32_e32 v19, v8
	s_nop 0
	v_add_u32_e32 v29, -1, v19
	v_add_u32_e32 v34, 1, v19
	v_fma_f32 v35, -v29, v19, v8
	v_fma_f32 v36, -v34, v19, v8
	v_cmp_ge_f32_e64 s[14:15], 0, v35
	s_nop 1
	v_cndmask_b32_e64 v19, v19, v29, s[14:15]
	v_cmp_lt_f32_e64 s[14:15], 0, v36
	s_nop 1
	v_cndmask_b32_e64 v19, v19, v34, s[14:15]
	v_mul_f32_e32 v29, 0x37800000, v19
	v_cndmask_b32_e32 v19, v19, v29, vcc
	v_cmp_class_f32_e32 vcc, v8, v192
	s_nop 1
	v_cndmask_b32_e32 v8, v19, v8, vcc
	v_div_scale_f32 v19, s[14:15], v8, v8, 1.0
	v_rcp_f32_e32 v34, v19
	v_div_scale_f32 v29, vcc, 1.0, v8, 1.0
	v_fma_f32 v35, -v19, v34, 1.0
	v_fmac_f32_e32 v34, v35, v34
	v_mul_f32_e32 v35, v29, v34
	v_fma_f32 v36, -v19, v35, v29
	v_fmac_f32_e32 v35, v36, v34
	v_fma_f32 v19, -v19, v35, v29
	v_div_fmas_f32 v19, v19, v34, v35
	v_div_fixup_f32 v8, v19, v8, 1.0
	v_mul_f32_e32 v20, v20, v8
	v_mul_f32_e32 v21, v21, v8
	v_mul_f32_e32 v30, v30, v8
	v_mul_f32_e32 v31, v31, v8
	v_mul_f32_e32 v20, v4, v20
	v_mul_f32_e32 v21, v5, v21
	v_mul_f32_e32 v30, v2, v30
	v_mul_f32_e32 v31, v3, v31
	v_cvt_pk_bf16_f32 v32, v20, v21
	v_cvt_pk_bf16_f32 v33, v30, v31
	s_add_u32 s14, s52, 0x1e000
	s_addc_u32 s15, s53, 0
	global_store_dwordx2 v184, v[32:33], s[14:15]
	s_add_u32 s4, s96, 0x15000
	s_addc_u32 s5, s97, 0
	s_add_u32 s6, s98, 0x15000
	s_addc_u32 s7, s99, 0
	global_load_dwordx2 v[56:57], v184, s[4:5] offset:-4096
	global_load_dwordx2 v[58:59], v184, s[6:7] offset:-4096
	global_load_dwordx2 v[60:61], v184, s[4:5]
	global_load_dwordx2 v[62:63], v184, s[6:7]
	s_add_u32 s4, s4, 0x2000
	s_addc_u32 s5, s5, 0
	s_add_u32 s6, s6, 0x2000
	s_addc_u32 s7, s7, 0
	global_load_dwordx2 v[64:65], v184, s[4:5] offset:-4096
	global_load_dwordx2 v[66:67], v184, s[6:7] offset:-4096
	global_load_dwordx2 v[68:69], v184, s[4:5]
	global_load_dwordx2 v[70:71], v184, s[6:7]
	s_waitcnt vmcnt(12)
	v_lshlrev_b32_e32 v8, 16, v40
	v_lshlrev_b32_e32 v19, 16, v42
	v_and_b32_e32 v29, 0xffff0000, v40
	v_and_b32_e32 v34, 0xffff0000, v42
	v_fma_f32 v20, -v18, v19, v8
	v_fma_f32 v21, -v18, v34, v29
	v_lshlrev_b32_e32 v8, 16, v41
	v_lshlrev_b32_e32 v19, 16, v43
	v_and_b32_e32 v29, 0xffff0000, v41
	v_and_b32_e32 v34, 0xffff0000, v43
	v_fma_f32 v30, -v18, v19, v8
	v_fma_f32 v31, -v18, v34, v29
	v_mul_f32_e32 v8, v21, v21
	v_mul_f32_e32 v19, v31, v31
	v_fmac_f32_e32 v8, v20, v20
	v_fmac_f32_e32 v19, v30, v30
	v_add_f32_e32 v8, v8, v19
	s_nop 1
	v_add_f32_dpp v8, v8, v8 quad_perm:[1,0,3,2] row_mask:0xf bank_mask:0xf
	s_nop 1
	v_add_f32_dpp v8, v8, v8 quad_perm:[2,3,0,1] row_mask:0xf bank_mask:0xf
	s_nop 1
	v_add_f32_dpp v8, v8, v8 row_half_mirror row_mask:0xf bank_mask:0xf
	s_nop 1
	v_add_f32_dpp v8, v8, v8 row_mirror row_mask:0xf bank_mask:0xf
	s_nop 1
	v_readlane_b32 s14, v8, 0
	v_readlane_b32 s15, v8, 16
	v_readlane_b32 s24, v8, 32
	v_readlane_b32 s25, v8, 48
	s_nop 2
	v_mov_b32_e32 v19, s15
	v_mov_b32_e32 v29, s25
	v_add_f32_e32 v19, s14, v19
	v_add_f32_e32 v29, s24, v29
	v_add_f32_e32 v8, v19, v29
	v_fmamk_f32 v8, v8, 0x3b800000, v191
	v_mul_f32_e32 v19, 0x4f800000, v8
	v_cmp_gt_f32_e32 vcc, s76, v8
	s_nop 1
	v_cndmask_b32_e32 v8, v8, v19, vcc
	v_sqrt_f32_e32 v19, v8
	s_nop 0
	v_add_u32_e32 v29, -1, v19
	v_add_u32_e32 v34, 1, v19
	v_fma_f32 v35, -v29, v19, v8
	v_fma_f32 v36, -v34, v19, v8
	v_cmp_ge_f32_e64 s[14:15], 0, v35
	s_nop 1
	v_cndmask_b32_e64 v19, v19, v29, s[14:15]
	v_cmp_lt_f32_e64 s[14:15], 0, v36
	s_nop 1
	v_cndmask_b32_e64 v19, v19, v34, s[14:15]
	v_mul_f32_e32 v29, 0x37800000, v19
	v_cndmask_b32_e32 v19, v19, v29, vcc
	v_cmp_class_f32_e32 vcc, v8, v192
	s_nop 1
	v_cndmask_b32_e32 v8, v19, v8, vcc
	v_div_scale_f32 v19, s[14:15], v8, v8, 1.0
	v_rcp_f32_e32 v34, v19
	v_div_scale_f32 v29, vcc, 1.0, v8, 1.0
	v_fma_f32 v35, -v19, v34, 1.0
	v_fmac_f32_e32 v34, v35, v34
	v_mul_f32_e32 v35, v29, v34
	v_fma_f32 v36, -v19, v35, v29
	v_fmac_f32_e32 v35, v36, v34
	v_fma_f32 v19, -v19, v35, v29
	v_div_fmas_f32 v19, v19, v34, v35
	v_div_fixup_f32 v8, v19, v8, 1.0
	v_mul_f32_e32 v20, v20, v8
	v_mul_f32_e32 v21, v21, v8
	v_mul_f32_e32 v30, v30, v8
	v_mul_f32_e32 v31, v31, v8
	v_mul_f32_e32 v20, v4, v20
	v_mul_f32_e32 v21, v5, v21
	v_mul_f32_e32 v30, v2, v30
	v_mul_f32_e32 v31, v3, v31
	v_cvt_pk_bf16_f32 v32, v20, v21
	v_cvt_pk_bf16_f32 v33, v30, v31
	s_add_i32 s14, s50, 16
	s_and_b32 s14, s14, 0xfc
	s_or_b32 s14, s14, s48
	s_mov_b32 s15, s49
	s_lshl_b64 s[14:15], s[14:15], 13
	v_lshl_add_u64 v[10:11], v[0:1], 0, s[14:15]
	global_store_dwordx2 v[10:11], v[32:33], off
	v_lshlrev_b32_e32 v8, 16, v44
	v_lshlrev_b32_e32 v19, 16, v46
	v_and_b32_e32 v29, 0xffff0000, v44
	v_and_b32_e32 v34, 0xffff0000, v46
	v_fma_f32 v20, -v18, v19, v8
	v_fma_f32 v21, -v18, v34, v29
	v_lshlrev_b32_e32 v8, 16, v45
	v_lshlrev_b32_e32 v19, 16, v47
	v_and_b32_e32 v29, 0xffff0000, v45
	v_and_b32_e32 v34, 0xffff0000, v47
	v_fma_f32 v30, -v18, v19, v8
	v_fma_f32 v31, -v18, v34, v29
	v_mul_f32_e32 v8, v21, v21
	v_mul_f32_e32 v19, v31, v31
	v_fmac_f32_e32 v8, v20, v20
	v_fmac_f32_e32 v19, v30, v30
	v_add_f32_e32 v8, v8, v19
	s_nop 1
	v_add_f32_dpp v8, v8, v8 quad_perm:[1,0,3,2] row_mask:0xf bank_mask:0xf
	s_nop 1
	v_add_f32_dpp v8, v8, v8 quad_perm:[2,3,0,1] row_mask:0xf bank_mask:0xf
	s_nop 1
	v_add_f32_dpp v8, v8, v8 row_half_mirror row_mask:0xf bank_mask:0xf
	s_nop 1
	v_add_f32_dpp v8, v8, v8 row_mirror row_mask:0xf bank_mask:0xf
	s_nop 1
	v_readlane_b32 s14, v8, 0
	v_readlane_b32 s15, v8, 16
	v_readlane_b32 s24, v8, 32
	v_readlane_b32 s25, v8, 48
	s_nop 2
	v_mov_b32_e32 v19, s15
	v_mov_b32_e32 v29, s25
	v_add_f32_e32 v19, s14, v19
	v_add_f32_e32 v29, s24, v29
	v_add_f32_e32 v8, v19, v29
	v_fmamk_f32 v8, v8, 0x3b800000, v191
	v_mul_f32_e32 v19, 0x4f800000, v8
	v_cmp_gt_f32_e32 vcc, s76, v8
	s_nop 1
	v_cndmask_b32_e32 v8, v8, v19, vcc
	v_sqrt_f32_e32 v19, v8
	s_nop 0
	v_add_u32_e32 v29, -1, v19
	v_add_u32_e32 v34, 1, v19
	v_fma_f32 v35, -v29, v19, v8
	v_fma_f32 v36, -v34, v19, v8
	v_cmp_ge_f32_e64 s[14:15], 0, v35
	s_nop 1
	v_cndmask_b32_e64 v19, v19, v29, s[14:15]
	v_cmp_lt_f32_e64 s[14:15], 0, v36
	s_nop 1
	v_cndmask_b32_e64 v19, v19, v34, s[14:15]
	v_mul_f32_e32 v29, 0x37800000, v19
	v_cndmask_b32_e32 v19, v19, v29, vcc
	v_cmp_class_f32_e32 vcc, v8, v192
	s_nop 1
	v_cndmask_b32_e32 v8, v19, v8, vcc
	v_div_scale_f32 v19, s[14:15], v8, v8, 1.0
	v_rcp_f32_e32 v34, v19
	v_div_scale_f32 v29, vcc, 1.0, v8, 1.0
	v_fma_f32 v35, -v19, v34, 1.0
	v_fmac_f32_e32 v34, v35, v34
	v_mul_f32_e32 v35, v29, v34
	v_fma_f32 v36, -v19, v35, v29
	v_fmac_f32_e32 v35, v36, v34
	v_fma_f32 v19, -v19, v35, v29
	v_div_fmas_f32 v19, v19, v34, v35
	v_div_fixup_f32 v8, v19, v8, 1.0
	v_mul_f32_e32 v20, v20, v8
	v_mul_f32_e32 v21, v21, v8
	v_mul_f32_e32 v30, v30, v8
	v_mul_f32_e32 v31, v31, v8
	v_mul_f32_e32 v20, v4, v20
	v_mul_f32_e32 v21, v5, v21
	v_mul_f32_e32 v30, v2, v30
	v_mul_f32_e32 v31, v3, v31
	v_cvt_pk_bf16_f32 v32, v20, v21
	v_cvt_pk_bf16_f32 v33, v30, v31
	s_add_u32 s14, s52, 0x22000
	s_addc_u32 s15, s53, 0
	global_store_dwordx2 v184, v[32:33], s[14:15]
	v_lshlrev_b32_e32 v8, 16, v48
	v_lshlrev_b32_e32 v19, 16, v50
	v_and_b32_e32 v29, 0xffff0000, v48
	v_and_b32_e32 v34, 0xffff0000, v50
	v_fma_f32 v20, -v18, v19, v8
	v_fma_f32 v21, -v18, v34, v29
	v_lshlrev_b32_e32 v8, 16, v49
	v_lshlrev_b32_e32 v19, 16, v51
	v_and_b32_e32 v29, 0xffff0000, v49
	v_and_b32_e32 v34, 0xffff0000, v51
	v_fma_f32 v30, -v18, v19, v8
	v_fma_f32 v31, -v18, v34, v29
	v_mul_f32_e32 v8, v21, v21
	v_mul_f32_e32 v19, v31, v31
	v_fmac_f32_e32 v8, v20, v20
	v_fmac_f32_e32 v19, v30, v30
	v_add_f32_e32 v8, v8, v19
	s_nop 1
	v_add_f32_dpp v8, v8, v8 quad_perm:[1,0,3,2] row_mask:0xf bank_mask:0xf
	s_nop 1
	v_add_f32_dpp v8, v8, v8 quad_perm:[2,3,0,1] row_mask:0xf bank_mask:0xf
	s_nop 1
	v_add_f32_dpp v8, v8, v8 row_half_mirror row_mask:0xf bank_mask:0xf
	s_nop 1
	v_add_f32_dpp v8, v8, v8 row_mirror row_mask:0xf bank_mask:0xf
	s_nop 1
	v_readlane_b32 s14, v8, 0
	v_readlane_b32 s15, v8, 16
	v_readlane_b32 s24, v8, 32
	v_readlane_b32 s25, v8, 48
	s_nop 2
	v_mov_b32_e32 v19, s15
	v_mov_b32_e32 v29, s25
	v_add_f32_e32 v19, s14, v19
	v_add_f32_e32 v29, s24, v29
	v_add_f32_e32 v8, v19, v29
	v_fmamk_f32 v8, v8, 0x3b800000, v191
	v_mul_f32_e32 v19, 0x4f800000, v8
	v_cmp_gt_f32_e32 vcc, s76, v8
	s_nop 1
	v_cndmask_b32_e32 v8, v8, v19, vcc
	v_sqrt_f32_e32 v19, v8
	s_nop 0
	v_add_u32_e32 v29, -1, v19
	v_add_u32_e32 v34, 1, v19
	v_fma_f32 v35, -v29, v19, v8
	v_fma_f32 v36, -v34, v19, v8
	v_cmp_ge_f32_e64 s[14:15], 0, v35
	s_nop 1
	v_cndmask_b32_e64 v19, v19, v29, s[14:15]
	v_cmp_lt_f32_e64 s[14:15], 0, v36
	s_nop 1
	v_cndmask_b32_e64 v19, v19, v34, s[14:15]
	v_mul_f32_e32 v29, 0x37800000, v19
	v_cndmask_b32_e32 v19, v19, v29, vcc
	v_cmp_class_f32_e32 vcc, v8, v192
	s_nop 1
	v_cndmask_b32_e32 v8, v19, v8, vcc
	v_div_scale_f32 v19, s[14:15], v8, v8, 1.0
	v_rcp_f32_e32 v34, v19
	v_div_scale_f32 v29, vcc, 1.0, v8, 1.0
	v_fma_f32 v35, -v19, v34, 1.0
	v_fmac_f32_e32 v34, v35, v34
	v_mul_f32_e32 v35, v29, v34
	v_fma_f32 v36, -v19, v35, v29
	v_fmac_f32_e32 v35, v36, v34
	v_fma_f32 v19, -v19, v35, v29
	v_div_fmas_f32 v19, v19, v34, v35
	v_div_fixup_f32 v8, v19, v8, 1.0
	v_mul_f32_e32 v20, v20, v8
	v_mul_f32_e32 v21, v21, v8
	v_mul_f32_e32 v30, v30, v8
	v_mul_f32_e32 v31, v31, v8
	v_mul_f32_e32 v20, v4, v20
	v_mul_f32_e32 v21, v5, v21
	v_mul_f32_e32 v30, v2, v30
	v_mul_f32_e32 v31, v3, v31
	v_cvt_pk_bf16_f32 v32, v20, v21
	v_cvt_pk_bf16_f32 v33, v30, v31
	s_add_i32 s14, s50, 18
	s_and_b32 s14, s14, 0xfe
	s_or_b32 s14, s14, s48
	s_mov_b32 s15, s49
	s_lshl_b64 s[14:15], s[14:15], 13
	v_lshl_add_u64 v[10:11], v[0:1], 0, s[14:15]
	global_store_dwordx2 v[10:11], v[32:33], off
	v_lshlrev_b32_e32 v8, 16, v52
	v_lshlrev_b32_e32 v19, 16, v54
	v_and_b32_e32 v29, 0xffff0000, v52
	v_and_b32_e32 v34, 0xffff0000, v54
	v_fma_f32 v20, -v18, v19, v8
	v_fma_f32 v21, -v18, v34, v29
	v_lshlrev_b32_e32 v8, 16, v53
	v_lshlrev_b32_e32 v19, 16, v55
	v_and_b32_e32 v29, 0xffff0000, v53
	v_and_b32_e32 v34, 0xffff0000, v55
	v_fma_f32 v30, -v18, v19, v8
	v_fma_f32 v31, -v18, v34, v29
	v_mul_f32_e32 v8, v21, v21
	v_mul_f32_e32 v19, v31, v31
	v_fmac_f32_e32 v8, v20, v20
	v_fmac_f32_e32 v19, v30, v30
	v_add_f32_e32 v8, v8, v19
	s_nop 1
	v_add_f32_dpp v8, v8, v8 quad_perm:[1,0,3,2] row_mask:0xf bank_mask:0xf
	s_nop 1
	v_add_f32_dpp v8, v8, v8 quad_perm:[2,3,0,1] row_mask:0xf bank_mask:0xf
	s_nop 1
	v_add_f32_dpp v8, v8, v8 row_half_mirror row_mask:0xf bank_mask:0xf
	s_nop 1
	v_add_f32_dpp v8, v8, v8 row_mirror row_mask:0xf bank_mask:0xf
	s_nop 1
	v_readlane_b32 s14, v8, 0
	v_readlane_b32 s15, v8, 16
	v_readlane_b32 s24, v8, 32
	v_readlane_b32 s25, v8, 48
	s_nop 2
	v_mov_b32_e32 v19, s15
	v_mov_b32_e32 v29, s25
	v_add_f32_e32 v19, s14, v19
	v_add_f32_e32 v29, s24, v29
	v_add_f32_e32 v8, v19, v29
	v_fmamk_f32 v8, v8, 0x3b800000, v191
	v_mul_f32_e32 v19, 0x4f800000, v8
	v_cmp_gt_f32_e32 vcc, s76, v8
	s_nop 1
	v_cndmask_b32_e32 v8, v8, v19, vcc
	v_sqrt_f32_e32 v19, v8
	s_nop 0
	v_add_u32_e32 v29, -1, v19
	v_add_u32_e32 v34, 1, v19
	v_fma_f32 v35, -v29, v19, v8
	v_fma_f32 v36, -v34, v19, v8
	v_cmp_ge_f32_e64 s[14:15], 0, v35
	s_nop 1
	v_cndmask_b32_e64 v19, v19, v29, s[14:15]
	v_cmp_lt_f32_e64 s[14:15], 0, v36
	s_nop 1
	v_cndmask_b32_e64 v19, v19, v34, s[14:15]
	v_mul_f32_e32 v29, 0x37800000, v19
	v_cndmask_b32_e32 v19, v19, v29, vcc
	v_cmp_class_f32_e32 vcc, v8, v192
	s_nop 1
	v_cndmask_b32_e32 v8, v19, v8, vcc
	v_div_scale_f32 v19, s[14:15], v8, v8, 1.0
	v_rcp_f32_e32 v34, v19
	v_div_scale_f32 v29, vcc, 1.0, v8, 1.0
	v_fma_f32 v35, -v19, v34, 1.0
	v_fmac_f32_e32 v34, v35, v34
	v_mul_f32_e32 v35, v29, v34
	v_fma_f32 v36, -v19, v35, v29
	v_fmac_f32_e32 v35, v36, v34
	v_fma_f32 v19, -v19, v35, v29
	v_div_fmas_f32 v19, v19, v34, v35
	v_div_fixup_f32 v8, v19, v8, 1.0
	v_mul_f32_e32 v20, v20, v8
	v_mul_f32_e32 v21, v21, v8
	v_mul_f32_e32 v30, v30, v8
	v_mul_f32_e32 v31, v31, v8
	v_mul_f32_e32 v20, v4, v20
	v_mul_f32_e32 v21, v5, v21
	v_mul_f32_e32 v30, v2, v30
	v_mul_f32_e32 v31, v3, v31
	v_cvt_pk_bf16_f32 v32, v20, v21
	v_cvt_pk_bf16_f32 v33, v30, v31
	s_add_u32 s14, s52, 0x26000
	s_addc_u32 s15, s53, 0
	global_store_dwordx2 v184, v[32:33], s[14:15]
	s_add_u32 s4, s96, 0x19000
	s_addc_u32 s5, s97, 0
	s_add_u32 s6, s98, 0x19000
	s_addc_u32 s7, s99, 0
	global_load_dwordx2 v[40:41], v184, s[4:5] offset:-4096
	global_load_dwordx2 v[42:43], v184, s[6:7] offset:-4096
	global_load_dwordx2 v[44:45], v184, s[4:5]
	global_load_dwordx2 v[46:47], v184, s[6:7]
	s_add_u32 s4, s4, 0x2000
	s_addc_u32 s5, s5, 0
	s_add_u32 s6, s6, 0x2000
	s_addc_u32 s7, s7, 0
	global_load_dwordx2 v[48:49], v184, s[4:5] offset:-4096
	global_load_dwordx2 v[50:51], v184, s[6:7] offset:-4096
	global_load_dwordx2 v[52:53], v184, s[4:5]
	global_load_dwordx2 v[54:55], v184, s[6:7]
	s_waitcnt vmcnt(12)
	v_lshlrev_b32_e32 v8, 16, v56
	v_lshlrev_b32_e32 v19, 16, v58
	v_and_b32_e32 v29, 0xffff0000, v56
	v_and_b32_e32 v34, 0xffff0000, v58
	v_fma_f32 v20, -v18, v19, v8
	v_fma_f32 v21, -v18, v34, v29
	v_lshlrev_b32_e32 v8, 16, v57
	v_lshlrev_b32_e32 v19, 16, v59
	v_and_b32_e32 v29, 0xffff0000, v57
	v_and_b32_e32 v34, 0xffff0000, v59
	v_fma_f32 v30, -v18, v19, v8
	v_fma_f32 v31, -v18, v34, v29
	v_mul_f32_e32 v8, v21, v21
	v_mul_f32_e32 v19, v31, v31
	v_fmac_f32_e32 v8, v20, v20
	v_fmac_f32_e32 v19, v30, v30
	v_add_f32_e32 v8, v8, v19
	s_nop 1
	v_add_f32_dpp v8, v8, v8 quad_perm:[1,0,3,2] row_mask:0xf bank_mask:0xf
	s_nop 1
	v_add_f32_dpp v8, v8, v8 quad_perm:[2,3,0,1] row_mask:0xf bank_mask:0xf
	s_nop 1
	v_add_f32_dpp v8, v8, v8 row_half_mirror row_mask:0xf bank_mask:0xf
	s_nop 1
	v_add_f32_dpp v8, v8, v8 row_mirror row_mask:0xf bank_mask:0xf
	s_nop 1
	v_readlane_b32 s14, v8, 0
	v_readlane_b32 s15, v8, 16
	v_readlane_b32 s24, v8, 32
	v_readlane_b32 s25, v8, 48
	s_nop 2
	v_mov_b32_e32 v19, s15
	v_mov_b32_e32 v29, s25
	v_add_f32_e32 v19, s14, v19
	v_add_f32_e32 v29, s24, v29
	v_add_f32_e32 v8, v19, v29
	v_fmamk_f32 v8, v8, 0x3b800000, v191
	v_mul_f32_e32 v19, 0x4f800000, v8
	v_cmp_gt_f32_e32 vcc, s76, v8
	s_nop 1
	v_cndmask_b32_e32 v8, v8, v19, vcc
	v_sqrt_f32_e32 v19, v8
	s_nop 0
	v_add_u32_e32 v29, -1, v19
	v_add_u32_e32 v34, 1, v19
	v_fma_f32 v35, -v29, v19, v8
	v_fma_f32 v36, -v34, v19, v8
	v_cmp_ge_f32_e64 s[14:15], 0, v35
	s_nop 1
	v_cndmask_b32_e64 v19, v19, v29, s[14:15]
	v_cmp_lt_f32_e64 s[14:15], 0, v36
	s_nop 1
	v_cndmask_b32_e64 v19, v19, v34, s[14:15]
	v_mul_f32_e32 v29, 0x37800000, v19
	v_cndmask_b32_e32 v19, v19, v29, vcc
	v_cmp_class_f32_e32 vcc, v8, v192
	s_nop 1
	v_cndmask_b32_e32 v8, v19, v8, vcc
	v_div_scale_f32 v19, s[14:15], v8, v8, 1.0
	v_rcp_f32_e32 v34, v19
	v_div_scale_f32 v29, vcc, 1.0, v8, 1.0
	v_fma_f32 v35, -v19, v34, 1.0
	v_fmac_f32_e32 v34, v35, v34
	v_mul_f32_e32 v35, v29, v34
	v_fma_f32 v36, -v19, v35, v29
	v_fmac_f32_e32 v35, v36, v34
	v_fma_f32 v19, -v19, v35, v29
	v_div_fmas_f32 v19, v19, v34, v35
	v_div_fixup_f32 v8, v19, v8, 1.0
	v_mul_f32_e32 v20, v20, v8
	v_mul_f32_e32 v21, v21, v8
	v_mul_f32_e32 v30, v30, v8
	v_mul_f32_e32 v31, v31, v8
	v_mul_f32_e32 v20, v4, v20
	v_mul_f32_e32 v21, v5, v21
	v_mul_f32_e32 v30, v2, v30
	v_mul_f32_e32 v31, v3, v31
	v_cvt_pk_bf16_f32 v32, v20, v21
	v_cvt_pk_bf16_f32 v33, v30, v31
	s_add_i32 s14, s50, 20
	s_and_b32 s14, s14, 0xfc
	s_or_b32 s14, s14, s48
	s_mov_b32 s15, s49
	s_lshl_b64 s[14:15], s[14:15], 13
	v_lshl_add_u64 v[10:11], v[0:1], 0, s[14:15]
	global_store_dwordx2 v[10:11], v[32:33], off
	v_lshlrev_b32_e32 v8, 16, v60
	v_lshlrev_b32_e32 v19, 16, v62
	v_and_b32_e32 v29, 0xffff0000, v60
	v_and_b32_e32 v34, 0xffff0000, v62
	v_fma_f32 v20, -v18, v19, v8
	v_fma_f32 v21, -v18, v34, v29
	v_lshlrev_b32_e32 v8, 16, v61
	v_lshlrev_b32_e32 v19, 16, v63
	v_and_b32_e32 v29, 0xffff0000, v61
	v_and_b32_e32 v34, 0xffff0000, v63
	v_fma_f32 v30, -v18, v19, v8
	v_fma_f32 v31, -v18, v34, v29
	v_mul_f32_e32 v8, v21, v21
	v_mul_f32_e32 v19, v31, v31
	v_fmac_f32_e32 v8, v20, v20
	v_fmac_f32_e32 v19, v30, v30
	v_add_f32_e32 v8, v8, v19
	s_nop 1
	v_add_f32_dpp v8, v8, v8 quad_perm:[1,0,3,2] row_mask:0xf bank_mask:0xf
	s_nop 1
	v_add_f32_dpp v8, v8, v8 quad_perm:[2,3,0,1] row_mask:0xf bank_mask:0xf
	s_nop 1
	v_add_f32_dpp v8, v8, v8 row_half_mirror row_mask:0xf bank_mask:0xf
	s_nop 1
	v_add_f32_dpp v8, v8, v8 row_mirror row_mask:0xf bank_mask:0xf
	s_nop 1
	v_readlane_b32 s14, v8, 0
	v_readlane_b32 s15, v8, 16
	v_readlane_b32 s24, v8, 32
	v_readlane_b32 s25, v8, 48
	s_nop 2
	v_mov_b32_e32 v19, s15
	v_mov_b32_e32 v29, s25
	v_add_f32_e32 v19, s14, v19
	v_add_f32_e32 v29, s24, v29
	v_add_f32_e32 v8, v19, v29
	v_fmamk_f32 v8, v8, 0x3b800000, v191
	v_mul_f32_e32 v19, 0x4f800000, v8
	v_cmp_gt_f32_e32 vcc, s76, v8
	s_nop 1
	v_cndmask_b32_e32 v8, v8, v19, vcc
	v_sqrt_f32_e32 v19, v8
	s_nop 0
	v_add_u32_e32 v29, -1, v19
	v_add_u32_e32 v34, 1, v19
	v_fma_f32 v35, -v29, v19, v8
	v_fma_f32 v36, -v34, v19, v8
	v_cmp_ge_f32_e64 s[14:15], 0, v35
	s_nop 1
	v_cndmask_b32_e64 v19, v19, v29, s[14:15]
	v_cmp_lt_f32_e64 s[14:15], 0, v36
	s_nop 1
	v_cndmask_b32_e64 v19, v19, v34, s[14:15]
	v_mul_f32_e32 v29, 0x37800000, v19
	v_cndmask_b32_e32 v19, v19, v29, vcc
	v_cmp_class_f32_e32 vcc, v8, v192
	s_nop 1
	v_cndmask_b32_e32 v8, v19, v8, vcc
	v_div_scale_f32 v19, s[14:15], v8, v8, 1.0
	v_rcp_f32_e32 v34, v19
	v_div_scale_f32 v29, vcc, 1.0, v8, 1.0
	v_fma_f32 v35, -v19, v34, 1.0
	v_fmac_f32_e32 v34, v35, v34
	v_mul_f32_e32 v35, v29, v34
	v_fma_f32 v36, -v19, v35, v29
	v_fmac_f32_e32 v35, v36, v34
	v_fma_f32 v19, -v19, v35, v29
	v_div_fmas_f32 v19, v19, v34, v35
	v_div_fixup_f32 v8, v19, v8, 1.0
	v_mul_f32_e32 v20, v20, v8
	v_mul_f32_e32 v21, v21, v8
	v_mul_f32_e32 v30, v30, v8
	v_mul_f32_e32 v31, v31, v8
	v_mul_f32_e32 v20, v4, v20
	v_mul_f32_e32 v21, v5, v21
	v_mul_f32_e32 v30, v2, v30
	v_mul_f32_e32 v31, v3, v31
	v_cvt_pk_bf16_f32 v32, v20, v21
	v_cvt_pk_bf16_f32 v33, v30, v31
	s_add_u32 s14, s52, 0x2a000
	s_addc_u32 s15, s53, 0
	global_store_dwordx2 v184, v[32:33], s[14:15]
	v_lshlrev_b32_e32 v8, 16, v64
	v_lshlrev_b32_e32 v19, 16, v66
	v_and_b32_e32 v29, 0xffff0000, v64
	v_and_b32_e32 v34, 0xffff0000, v66
	v_fma_f32 v20, -v18, v19, v8
	v_fma_f32 v21, -v18, v34, v29
	v_lshlrev_b32_e32 v8, 16, v65
	v_lshlrev_b32_e32 v19, 16, v67
	v_and_b32_e32 v29, 0xffff0000, v65
	v_and_b32_e32 v34, 0xffff0000, v67
	v_fma_f32 v30, -v18, v19, v8
	v_fma_f32 v31, -v18, v34, v29
	v_mul_f32_e32 v8, v21, v21
	v_mul_f32_e32 v19, v31, v31
	v_fmac_f32_e32 v8, v20, v20
	v_fmac_f32_e32 v19, v30, v30
	v_add_f32_e32 v8, v8, v19
	s_nop 1
	v_add_f32_dpp v8, v8, v8 quad_perm:[1,0,3,2] row_mask:0xf bank_mask:0xf
	s_nop 1
	v_add_f32_dpp v8, v8, v8 quad_perm:[2,3,0,1] row_mask:0xf bank_mask:0xf
	s_nop 1
	v_add_f32_dpp v8, v8, v8 row_half_mirror row_mask:0xf bank_mask:0xf
	s_nop 1
	v_add_f32_dpp v8, v8, v8 row_mirror row_mask:0xf bank_mask:0xf
	s_nop 1
	v_readlane_b32 s14, v8, 0
	v_readlane_b32 s15, v8, 16
	v_readlane_b32 s24, v8, 32
	v_readlane_b32 s25, v8, 48
	s_nop 2
	v_mov_b32_e32 v19, s15
	v_mov_b32_e32 v29, s25
	v_add_f32_e32 v19, s14, v19
	v_add_f32_e32 v29, s24, v29
	v_add_f32_e32 v8, v19, v29
	v_fmamk_f32 v8, v8, 0x3b800000, v191
	v_mul_f32_e32 v19, 0x4f800000, v8
	v_cmp_gt_f32_e32 vcc, s76, v8
	s_nop 1
	v_cndmask_b32_e32 v8, v8, v19, vcc
	v_sqrt_f32_e32 v19, v8
	s_nop 0
	v_add_u32_e32 v29, -1, v19
	v_add_u32_e32 v34, 1, v19
	v_fma_f32 v35, -v29, v19, v8
	v_fma_f32 v36, -v34, v19, v8
	v_cmp_ge_f32_e64 s[14:15], 0, v35
	s_nop 1
	v_cndmask_b32_e64 v19, v19, v29, s[14:15]
	v_cmp_lt_f32_e64 s[14:15], 0, v36
	s_nop 1
	v_cndmask_b32_e64 v19, v19, v34, s[14:15]
	v_mul_f32_e32 v29, 0x37800000, v19
	v_cndmask_b32_e32 v19, v19, v29, vcc
	v_cmp_class_f32_e32 vcc, v8, v192
	s_nop 1
	v_cndmask_b32_e32 v8, v19, v8, vcc
	v_div_scale_f32 v19, s[14:15], v8, v8, 1.0
	v_rcp_f32_e32 v34, v19
	v_div_scale_f32 v29, vcc, 1.0, v8, 1.0
	v_fma_f32 v35, -v19, v34, 1.0
	v_fmac_f32_e32 v34, v35, v34
	v_mul_f32_e32 v35, v29, v34
	v_fma_f32 v36, -v19, v35, v29
	v_fmac_f32_e32 v35, v36, v34
	v_fma_f32 v19, -v19, v35, v29
	v_div_fmas_f32 v19, v19, v34, v35
	v_div_fixup_f32 v8, v19, v8, 1.0
	v_mul_f32_e32 v20, v20, v8
	v_mul_f32_e32 v21, v21, v8
	v_mul_f32_e32 v30, v30, v8
	v_mul_f32_e32 v31, v31, v8
	v_mul_f32_e32 v20, v4, v20
	v_mul_f32_e32 v21, v5, v21
	v_mul_f32_e32 v30, v2, v30
	v_mul_f32_e32 v31, v3, v31
	v_cvt_pk_bf16_f32 v32, v20, v21
	v_cvt_pk_bf16_f32 v33, v30, v31
	s_add_i32 s14, s50, 22
	s_and_b32 s14, s14, 0xfe
	s_or_b32 s14, s14, s48
	s_mov_b32 s15, s49
	s_lshl_b64 s[14:15], s[14:15], 13
	v_lshl_add_u64 v[10:11], v[0:1], 0, s[14:15]
	global_store_dwordx2 v[10:11], v[32:33], off
	v_lshlrev_b32_e32 v8, 16, v68
	v_lshlrev_b32_e32 v19, 16, v70
	v_and_b32_e32 v29, 0xffff0000, v68
	v_and_b32_e32 v34, 0xffff0000, v70
	v_fma_f32 v20, -v18, v19, v8
	v_fma_f32 v21, -v18, v34, v29
	v_lshlrev_b32_e32 v8, 16, v69
	v_lshlrev_b32_e32 v19, 16, v71
	v_and_b32_e32 v29, 0xffff0000, v69
	v_and_b32_e32 v34, 0xffff0000, v71
	v_fma_f32 v30, -v18, v19, v8
	v_fma_f32 v31, -v18, v34, v29
	v_mul_f32_e32 v8, v21, v21
	v_mul_f32_e32 v19, v31, v31
	v_fmac_f32_e32 v8, v20, v20
	v_fmac_f32_e32 v19, v30, v30
	v_add_f32_e32 v8, v8, v19
	s_nop 1
	v_add_f32_dpp v8, v8, v8 quad_perm:[1,0,3,2] row_mask:0xf bank_mask:0xf
	s_nop 1
	v_add_f32_dpp v8, v8, v8 quad_perm:[2,3,0,1] row_mask:0xf bank_mask:0xf
	s_nop 1
	v_add_f32_dpp v8, v8, v8 row_half_mirror row_mask:0xf bank_mask:0xf
	s_nop 1
	v_add_f32_dpp v8, v8, v8 row_mirror row_mask:0xf bank_mask:0xf
	s_nop 1
	v_readlane_b32 s14, v8, 0
	v_readlane_b32 s15, v8, 16
	v_readlane_b32 s24, v8, 32
	v_readlane_b32 s25, v8, 48
	s_nop 2
	v_mov_b32_e32 v19, s15
	v_mov_b32_e32 v29, s25
	v_add_f32_e32 v19, s14, v19
	v_add_f32_e32 v29, s24, v29
	v_add_f32_e32 v8, v19, v29
	v_fmamk_f32 v8, v8, 0x3b800000, v191
	v_mul_f32_e32 v19, 0x4f800000, v8
	v_cmp_gt_f32_e32 vcc, s76, v8
	s_nop 1
	v_cndmask_b32_e32 v8, v8, v19, vcc
	v_sqrt_f32_e32 v19, v8
	s_nop 0
	v_add_u32_e32 v29, -1, v19
	v_add_u32_e32 v34, 1, v19
	v_fma_f32 v35, -v29, v19, v8
	v_fma_f32 v36, -v34, v19, v8
	v_cmp_ge_f32_e64 s[14:15], 0, v35
	s_nop 1
	v_cndmask_b32_e64 v19, v19, v29, s[14:15]
	v_cmp_lt_f32_e64 s[14:15], 0, v36
	s_nop 1
	v_cndmask_b32_e64 v19, v19, v34, s[14:15]
	v_mul_f32_e32 v29, 0x37800000, v19
	v_cndmask_b32_e32 v19, v19, v29, vcc
	v_cmp_class_f32_e32 vcc, v8, v192
	s_nop 1
	v_cndmask_b32_e32 v8, v19, v8, vcc
	v_div_scale_f32 v19, s[14:15], v8, v8, 1.0
	v_rcp_f32_e32 v34, v19
	v_div_scale_f32 v29, vcc, 1.0, v8, 1.0
	v_fma_f32 v35, -v19, v34, 1.0
	v_fmac_f32_e32 v34, v35, v34
	v_mul_f32_e32 v35, v29, v34
	v_fma_f32 v36, -v19, v35, v29
	v_fmac_f32_e32 v35, v36, v34
	v_fma_f32 v19, -v19, v35, v29
	v_div_fmas_f32 v19, v19, v34, v35
	v_div_fixup_f32 v8, v19, v8, 1.0
	v_mul_f32_e32 v20, v20, v8
	v_mul_f32_e32 v21, v21, v8
	v_mul_f32_e32 v30, v30, v8
	v_mul_f32_e32 v31, v31, v8
	v_mul_f32_e32 v20, v4, v20
	v_mul_f32_e32 v21, v5, v21
	v_mul_f32_e32 v30, v2, v30
	v_mul_f32_e32 v31, v3, v31
	v_cvt_pk_bf16_f32 v32, v20, v21
	v_cvt_pk_bf16_f32 v33, v30, v31
	s_add_u32 s14, s52, 0x2e000
	s_addc_u32 s15, s53, 0
	global_store_dwordx2 v184, v[32:33], s[14:15]
	s_add_u32 s4, s96, 0x1d000
	s_addc_u32 s5, s97, 0
	s_add_u32 s6, s98, 0x1d000
	s_addc_u32 s7, s99, 0
	global_load_dwordx2 v[56:57], v184, s[4:5] offset:-4096
	global_load_dwordx2 v[58:59], v184, s[6:7] offset:-4096
	global_load_dwordx2 v[60:61], v184, s[4:5]
	global_load_dwordx2 v[62:63], v184, s[6:7]
	s_add_u32 s4, s4, 0x2000
	s_addc_u32 s5, s5, 0
	s_add_u32 s6, s6, 0x2000
	s_addc_u32 s7, s7, 0
	global_load_dwordx2 v[64:65], v184, s[4:5] offset:-4096
	global_load_dwordx2 v[66:67], v184, s[6:7] offset:-4096
	global_load_dwordx2 v[68:69], v184, s[4:5]
	global_load_dwordx2 v[70:71], v184, s[6:7]
	s_waitcnt vmcnt(12)
	v_lshlrev_b32_e32 v8, 16, v40
	v_lshlrev_b32_e32 v19, 16, v42
	v_and_b32_e32 v29, 0xffff0000, v40
	v_and_b32_e32 v34, 0xffff0000, v42
	v_fma_f32 v20, -v18, v19, v8
	v_fma_f32 v21, -v18, v34, v29
	v_lshlrev_b32_e32 v8, 16, v41
	v_lshlrev_b32_e32 v19, 16, v43
	v_and_b32_e32 v29, 0xffff0000, v41
	v_and_b32_e32 v34, 0xffff0000, v43
	v_fma_f32 v30, -v18, v19, v8
	v_fma_f32 v31, -v18, v34, v29
	v_mul_f32_e32 v8, v21, v21
	v_mul_f32_e32 v19, v31, v31
	v_fmac_f32_e32 v8, v20, v20
	v_fmac_f32_e32 v19, v30, v30
	v_add_f32_e32 v8, v8, v19
	s_nop 1
	v_add_f32_dpp v8, v8, v8 quad_perm:[1,0,3,2] row_mask:0xf bank_mask:0xf
	s_nop 1
	v_add_f32_dpp v8, v8, v8 quad_perm:[2,3,0,1] row_mask:0xf bank_mask:0xf
	s_nop 1
	v_add_f32_dpp v8, v8, v8 row_half_mirror row_mask:0xf bank_mask:0xf
	s_nop 1
	v_add_f32_dpp v8, v8, v8 row_mirror row_mask:0xf bank_mask:0xf
	s_nop 1
	v_readlane_b32 s14, v8, 0
	v_readlane_b32 s15, v8, 16
	v_readlane_b32 s24, v8, 32
	v_readlane_b32 s25, v8, 48
	s_nop 2
	v_mov_b32_e32 v19, s15
	v_mov_b32_e32 v29, s25
	v_add_f32_e32 v19, s14, v19
	v_add_f32_e32 v29, s24, v29
	v_add_f32_e32 v8, v19, v29
	v_fmamk_f32 v8, v8, 0x3b800000, v191
	v_mul_f32_e32 v19, 0x4f800000, v8
	v_cmp_gt_f32_e32 vcc, s76, v8
	s_nop 1
	v_cndmask_b32_e32 v8, v8, v19, vcc
	v_sqrt_f32_e32 v19, v8
	s_nop 0
	v_add_u32_e32 v29, -1, v19
	v_add_u32_e32 v34, 1, v19
	v_fma_f32 v35, -v29, v19, v8
	v_fma_f32 v36, -v34, v19, v8
	v_cmp_ge_f32_e64 s[14:15], 0, v35
	s_nop 1
	v_cndmask_b32_e64 v19, v19, v29, s[14:15]
	v_cmp_lt_f32_e64 s[14:15], 0, v36
	s_nop 1
	v_cndmask_b32_e64 v19, v19, v34, s[14:15]
	v_mul_f32_e32 v29, 0x37800000, v19
	v_cndmask_b32_e32 v19, v19, v29, vcc
	v_cmp_class_f32_e32 vcc, v8, v192
	s_nop 1
	v_cndmask_b32_e32 v8, v19, v8, vcc
	v_div_scale_f32 v19, s[14:15], v8, v8, 1.0
	v_rcp_f32_e32 v34, v19
	v_div_scale_f32 v29, vcc, 1.0, v8, 1.0
	v_fma_f32 v35, -v19, v34, 1.0
	v_fmac_f32_e32 v34, v35, v34
	v_mul_f32_e32 v35, v29, v34
	v_fma_f32 v36, -v19, v35, v29
	v_fmac_f32_e32 v35, v36, v34
	v_fma_f32 v19, -v19, v35, v29
	v_div_fmas_f32 v19, v19, v34, v35
	v_div_fixup_f32 v8, v19, v8, 1.0
	v_mul_f32_e32 v20, v20, v8
	v_mul_f32_e32 v21, v21, v8
	v_mul_f32_e32 v30, v30, v8
	v_mul_f32_e32 v31, v31, v8
	v_mul_f32_e32 v20, v4, v20
	v_mul_f32_e32 v21, v5, v21
	v_mul_f32_e32 v30, v2, v30
	v_mul_f32_e32 v31, v3, v31
	v_cvt_pk_bf16_f32 v32, v20, v21
	v_cvt_pk_bf16_f32 v33, v30, v31
	s_add_i32 s14, s50, 24
	s_and_b32 s14, s14, 0xfc
	s_or_b32 s14, s14, s48
	s_mov_b32 s15, s49
	s_lshl_b64 s[14:15], s[14:15], 13
	v_lshl_add_u64 v[10:11], v[0:1], 0, s[14:15]
	global_store_dwordx2 v[10:11], v[32:33], off
	v_lshlrev_b32_e32 v8, 16, v44
	v_lshlrev_b32_e32 v19, 16, v46
	v_and_b32_e32 v29, 0xffff0000, v44
	v_and_b32_e32 v34, 0xffff0000, v46
	v_fma_f32 v20, -v18, v19, v8
	v_fma_f32 v21, -v18, v34, v29
	v_lshlrev_b32_e32 v8, 16, v45
	v_lshlrev_b32_e32 v19, 16, v47
	v_and_b32_e32 v29, 0xffff0000, v45
	v_and_b32_e32 v34, 0xffff0000, v47
	v_fma_f32 v30, -v18, v19, v8
	v_fma_f32 v31, -v18, v34, v29
	v_mul_f32_e32 v8, v21, v21
	v_mul_f32_e32 v19, v31, v31
	v_fmac_f32_e32 v8, v20, v20
	v_fmac_f32_e32 v19, v30, v30
	v_add_f32_e32 v8, v8, v19
	s_nop 1
	v_add_f32_dpp v8, v8, v8 quad_perm:[1,0,3,2] row_mask:0xf bank_mask:0xf
	s_nop 1
	v_add_f32_dpp v8, v8, v8 quad_perm:[2,3,0,1] row_mask:0xf bank_mask:0xf
	s_nop 1
	v_add_f32_dpp v8, v8, v8 row_half_mirror row_mask:0xf bank_mask:0xf
	s_nop 1
	v_add_f32_dpp v8, v8, v8 row_mirror row_mask:0xf bank_mask:0xf
	s_nop 1
	v_readlane_b32 s14, v8, 0
	v_readlane_b32 s15, v8, 16
	v_readlane_b32 s24, v8, 32
	v_readlane_b32 s25, v8, 48
	s_nop 2
	v_mov_b32_e32 v19, s15
	v_mov_b32_e32 v29, s25
	v_add_f32_e32 v19, s14, v19
	v_add_f32_e32 v29, s24, v29
	v_add_f32_e32 v8, v19, v29
	v_fmamk_f32 v8, v8, 0x3b800000, v191
	v_mul_f32_e32 v19, 0x4f800000, v8
	v_cmp_gt_f32_e32 vcc, s76, v8
	s_nop 1
	v_cndmask_b32_e32 v8, v8, v19, vcc
	v_sqrt_f32_e32 v19, v8
	s_nop 0
	v_add_u32_e32 v29, -1, v19
	v_add_u32_e32 v34, 1, v19
	v_fma_f32 v35, -v29, v19, v8
	v_fma_f32 v36, -v34, v19, v8
	v_cmp_ge_f32_e64 s[14:15], 0, v35
	s_nop 1
	v_cndmask_b32_e64 v19, v19, v29, s[14:15]
	v_cmp_lt_f32_e64 s[14:15], 0, v36
	s_nop 1
	v_cndmask_b32_e64 v19, v19, v34, s[14:15]
	v_mul_f32_e32 v29, 0x37800000, v19
	v_cndmask_b32_e32 v19, v19, v29, vcc
	v_cmp_class_f32_e32 vcc, v8, v192
	s_nop 1
	v_cndmask_b32_e32 v8, v19, v8, vcc
	v_div_scale_f32 v19, s[14:15], v8, v8, 1.0
	v_rcp_f32_e32 v34, v19
	v_div_scale_f32 v29, vcc, 1.0, v8, 1.0
	v_fma_f32 v35, -v19, v34, 1.0
	v_fmac_f32_e32 v34, v35, v34
	v_mul_f32_e32 v35, v29, v34
	v_fma_f32 v36, -v19, v35, v29
	v_fmac_f32_e32 v35, v36, v34
	v_fma_f32 v19, -v19, v35, v29
	v_div_fmas_f32 v19, v19, v34, v35
	v_div_fixup_f32 v8, v19, v8, 1.0
	v_mul_f32_e32 v20, v20, v8
	v_mul_f32_e32 v21, v21, v8
	v_mul_f32_e32 v30, v30, v8
	v_mul_f32_e32 v31, v31, v8
	v_mul_f32_e32 v20, v4, v20
	v_mul_f32_e32 v21, v5, v21
	v_mul_f32_e32 v30, v2, v30
	v_mul_f32_e32 v31, v3, v31
	v_cvt_pk_bf16_f32 v32, v20, v21
	v_cvt_pk_bf16_f32 v33, v30, v31
	s_add_u32 s14, s52, 0x32000
	s_addc_u32 s15, s53, 0
	global_store_dwordx2 v184, v[32:33], s[14:15]
	v_lshlrev_b32_e32 v8, 16, v48
	v_lshlrev_b32_e32 v19, 16, v50
	v_and_b32_e32 v29, 0xffff0000, v48
	v_and_b32_e32 v34, 0xffff0000, v50
	v_fma_f32 v20, -v18, v19, v8
	v_fma_f32 v21, -v18, v34, v29
	v_lshlrev_b32_e32 v8, 16, v49
	v_lshlrev_b32_e32 v19, 16, v51
	v_and_b32_e32 v29, 0xffff0000, v49
	v_and_b32_e32 v34, 0xffff0000, v51
	v_fma_f32 v30, -v18, v19, v8
	v_fma_f32 v31, -v18, v34, v29
	v_mul_f32_e32 v8, v21, v21
	v_mul_f32_e32 v19, v31, v31
	v_fmac_f32_e32 v8, v20, v20
	v_fmac_f32_e32 v19, v30, v30
	v_add_f32_e32 v8, v8, v19
	s_nop 1
	v_add_f32_dpp v8, v8, v8 quad_perm:[1,0,3,2] row_mask:0xf bank_mask:0xf
	s_nop 1
	v_add_f32_dpp v8, v8, v8 quad_perm:[2,3,0,1] row_mask:0xf bank_mask:0xf
	s_nop 1
	v_add_f32_dpp v8, v8, v8 row_half_mirror row_mask:0xf bank_mask:0xf
	s_nop 1
	v_add_f32_dpp v8, v8, v8 row_mirror row_mask:0xf bank_mask:0xf
	s_nop 1
	v_readlane_b32 s14, v8, 0
	v_readlane_b32 s15, v8, 16
	v_readlane_b32 s24, v8, 32
	v_readlane_b32 s25, v8, 48
	s_nop 2
	v_mov_b32_e32 v19, s15
	v_mov_b32_e32 v29, s25
	v_add_f32_e32 v19, s14, v19
	v_add_f32_e32 v29, s24, v29
	v_add_f32_e32 v8, v19, v29
	v_fmamk_f32 v8, v8, 0x3b800000, v191
	v_mul_f32_e32 v19, 0x4f800000, v8
	v_cmp_gt_f32_e32 vcc, s76, v8
	s_nop 1
	v_cndmask_b32_e32 v8, v8, v19, vcc
	v_sqrt_f32_e32 v19, v8
	s_nop 0
	v_add_u32_e32 v29, -1, v19
	v_add_u32_e32 v34, 1, v19
	v_fma_f32 v35, -v29, v19, v8
	v_fma_f32 v36, -v34, v19, v8
	v_cmp_ge_f32_e64 s[14:15], 0, v35
	s_nop 1
	v_cndmask_b32_e64 v19, v19, v29, s[14:15]
	v_cmp_lt_f32_e64 s[14:15], 0, v36
	s_nop 1
	v_cndmask_b32_e64 v19, v19, v34, s[14:15]
	v_mul_f32_e32 v29, 0x37800000, v19
	v_cndmask_b32_e32 v19, v19, v29, vcc
	v_cmp_class_f32_e32 vcc, v8, v192
	s_nop 1
	v_cndmask_b32_e32 v8, v19, v8, vcc
	v_div_scale_f32 v19, s[14:15], v8, v8, 1.0
	v_rcp_f32_e32 v34, v19
	v_div_scale_f32 v29, vcc, 1.0, v8, 1.0
	v_fma_f32 v35, -v19, v34, 1.0
	v_fmac_f32_e32 v34, v35, v34
	v_mul_f32_e32 v35, v29, v34
	v_fma_f32 v36, -v19, v35, v29
	v_fmac_f32_e32 v35, v36, v34
	v_fma_f32 v19, -v19, v35, v29
	v_div_fmas_f32 v19, v19, v34, v35
	v_div_fixup_f32 v8, v19, v8, 1.0
	v_mul_f32_e32 v20, v20, v8
	v_mul_f32_e32 v21, v21, v8
	v_mul_f32_e32 v30, v30, v8
	v_mul_f32_e32 v31, v31, v8
	v_mul_f32_e32 v20, v4, v20
	v_mul_f32_e32 v21, v5, v21
	v_mul_f32_e32 v30, v2, v30
	v_mul_f32_e32 v31, v3, v31
	v_cvt_pk_bf16_f32 v32, v20, v21
	v_cvt_pk_bf16_f32 v33, v30, v31
	s_add_i32 s14, s50, 26
	s_and_b32 s14, s14, 0xfe
	s_or_b32 s14, s14, s48
	s_mov_b32 s15, s49
	s_lshl_b64 s[14:15], s[14:15], 13
	v_lshl_add_u64 v[10:11], v[0:1], 0, s[14:15]
	global_store_dwordx2 v[10:11], v[32:33], off
	v_lshlrev_b32_e32 v8, 16, v52
	v_lshlrev_b32_e32 v19, 16, v54
	v_and_b32_e32 v29, 0xffff0000, v52
	v_and_b32_e32 v34, 0xffff0000, v54
	v_fma_f32 v20, -v18, v19, v8
	v_fma_f32 v21, -v18, v34, v29
	v_lshlrev_b32_e32 v8, 16, v53
	v_lshlrev_b32_e32 v19, 16, v55
	v_and_b32_e32 v29, 0xffff0000, v53
	v_and_b32_e32 v34, 0xffff0000, v55
	v_fma_f32 v30, -v18, v19, v8
	v_fma_f32 v31, -v18, v34, v29
	v_mul_f32_e32 v8, v21, v21
	v_mul_f32_e32 v19, v31, v31
	v_fmac_f32_e32 v8, v20, v20
	v_fmac_f32_e32 v19, v30, v30
	v_add_f32_e32 v8, v8, v19
	s_nop 1
	v_add_f32_dpp v8, v8, v8 quad_perm:[1,0,3,2] row_mask:0xf bank_mask:0xf
	s_nop 1
	v_add_f32_dpp v8, v8, v8 quad_perm:[2,3,0,1] row_mask:0xf bank_mask:0xf
	s_nop 1
	v_add_f32_dpp v8, v8, v8 row_half_mirror row_mask:0xf bank_mask:0xf
	s_nop 1
	v_add_f32_dpp v8, v8, v8 row_mirror row_mask:0xf bank_mask:0xf
	s_nop 1
	v_readlane_b32 s14, v8, 0
	v_readlane_b32 s15, v8, 16
	v_readlane_b32 s24, v8, 32
	v_readlane_b32 s25, v8, 48
	s_nop 2
	v_mov_b32_e32 v19, s15
	v_mov_b32_e32 v29, s25
	v_add_f32_e32 v19, s14, v19
	v_add_f32_e32 v29, s24, v29
	v_add_f32_e32 v8, v19, v29
	v_fmamk_f32 v8, v8, 0x3b800000, v191
	v_mul_f32_e32 v19, 0x4f800000, v8
	v_cmp_gt_f32_e32 vcc, s76, v8
	s_nop 1
	v_cndmask_b32_e32 v8, v8, v19, vcc
	v_sqrt_f32_e32 v19, v8
	s_nop 0
	v_add_u32_e32 v29, -1, v19
	v_add_u32_e32 v34, 1, v19
	v_fma_f32 v35, -v29, v19, v8
	v_fma_f32 v36, -v34, v19, v8
	v_cmp_ge_f32_e64 s[14:15], 0, v35
	s_nop 1
	v_cndmask_b32_e64 v19, v19, v29, s[14:15]
	v_cmp_lt_f32_e64 s[14:15], 0, v36
	s_nop 1
	v_cndmask_b32_e64 v19, v19, v34, s[14:15]
	v_mul_f32_e32 v29, 0x37800000, v19
	v_cndmask_b32_e32 v19, v19, v29, vcc
	v_cmp_class_f32_e32 vcc, v8, v192
	s_nop 1
	v_cndmask_b32_e32 v8, v19, v8, vcc
	v_div_scale_f32 v19, s[14:15], v8, v8, 1.0
	v_rcp_f32_e32 v34, v19
	v_div_scale_f32 v29, vcc, 1.0, v8, 1.0
	v_fma_f32 v35, -v19, v34, 1.0
	v_fmac_f32_e32 v34, v35, v34
	v_mul_f32_e32 v35, v29, v34
	v_fma_f32 v36, -v19, v35, v29
	v_fmac_f32_e32 v35, v36, v34
	v_fma_f32 v19, -v19, v35, v29
	v_div_fmas_f32 v19, v19, v34, v35
	v_div_fixup_f32 v8, v19, v8, 1.0
	v_mul_f32_e32 v20, v20, v8
	v_mul_f32_e32 v21, v21, v8
	v_mul_f32_e32 v30, v30, v8
	v_mul_f32_e32 v31, v31, v8
	v_mul_f32_e32 v20, v4, v20
	v_mul_f32_e32 v21, v5, v21
	v_mul_f32_e32 v30, v2, v30
	v_mul_f32_e32 v31, v3, v31
	v_cvt_pk_bf16_f32 v32, v20, v21
	v_cvt_pk_bf16_f32 v33, v30, v31
	s_add_u32 s14, s52, 0x36000
	s_addc_u32 s15, s53, 0
	global_store_dwordx2 v184, v[32:33], s[14:15]
	s_waitcnt vmcnt(4)
	v_lshlrev_b32_e32 v8, 16, v56
	v_lshlrev_b32_e32 v19, 16, v58
	v_and_b32_e32 v29, 0xffff0000, v56
	v_and_b32_e32 v34, 0xffff0000, v58
	v_fma_f32 v20, -v18, v19, v8
	v_fma_f32 v21, -v18, v34, v29
	v_lshlrev_b32_e32 v8, 16, v57
	v_lshlrev_b32_e32 v19, 16, v59
	v_and_b32_e32 v29, 0xffff0000, v57
	v_and_b32_e32 v34, 0xffff0000, v59
	v_fma_f32 v30, -v18, v19, v8
	v_fma_f32 v31, -v18, v34, v29
	v_mul_f32_e32 v8, v21, v21
	v_mul_f32_e32 v19, v31, v31
	v_fmac_f32_e32 v8, v20, v20
	v_fmac_f32_e32 v19, v30, v30
	v_add_f32_e32 v8, v8, v19
	s_nop 1
	v_add_f32_dpp v8, v8, v8 quad_perm:[1,0,3,2] row_mask:0xf bank_mask:0xf
	s_nop 1
	v_add_f32_dpp v8, v8, v8 quad_perm:[2,3,0,1] row_mask:0xf bank_mask:0xf
	s_nop 1
	v_add_f32_dpp v8, v8, v8 row_half_mirror row_mask:0xf bank_mask:0xf
	s_nop 1
	v_add_f32_dpp v8, v8, v8 row_mirror row_mask:0xf bank_mask:0xf
	s_nop 1
	v_readlane_b32 s14, v8, 0
	v_readlane_b32 s15, v8, 16
	v_readlane_b32 s24, v8, 32
	v_readlane_b32 s25, v8, 48
	s_nop 2
	v_mov_b32_e32 v19, s15
	v_mov_b32_e32 v29, s25
	v_add_f32_e32 v19, s14, v19
	v_add_f32_e32 v29, s24, v29
	v_add_f32_e32 v8, v19, v29
	v_fmamk_f32 v8, v8, 0x3b800000, v191
	v_mul_f32_e32 v19, 0x4f800000, v8
	v_cmp_gt_f32_e32 vcc, s76, v8
	s_nop 1
	v_cndmask_b32_e32 v8, v8, v19, vcc
	v_sqrt_f32_e32 v19, v8
	s_nop 0
	v_add_u32_e32 v29, -1, v19
	v_add_u32_e32 v34, 1, v19
	v_fma_f32 v35, -v29, v19, v8
	v_fma_f32 v36, -v34, v19, v8
	v_cmp_ge_f32_e64 s[14:15], 0, v35
	s_nop 1
	v_cndmask_b32_e64 v19, v19, v29, s[14:15]
	v_cmp_lt_f32_e64 s[14:15], 0, v36
	s_nop 1
	v_cndmask_b32_e64 v19, v19, v34, s[14:15]
	v_mul_f32_e32 v29, 0x37800000, v19
	v_cndmask_b32_e32 v19, v19, v29, vcc
	v_cmp_class_f32_e32 vcc, v8, v192
	s_nop 1
	v_cndmask_b32_e32 v8, v19, v8, vcc
	v_div_scale_f32 v19, s[14:15], v8, v8, 1.0
	v_rcp_f32_e32 v34, v19
	v_div_scale_f32 v29, vcc, 1.0, v8, 1.0
	v_fma_f32 v35, -v19, v34, 1.0
	v_fmac_f32_e32 v34, v35, v34
	v_mul_f32_e32 v35, v29, v34
	v_fma_f32 v36, -v19, v35, v29
	v_fmac_f32_e32 v35, v36, v34
	v_fma_f32 v19, -v19, v35, v29
	v_div_fmas_f32 v19, v19, v34, v35
	v_div_fixup_f32 v8, v19, v8, 1.0
	v_mul_f32_e32 v20, v20, v8
	v_mul_f32_e32 v21, v21, v8
	v_mul_f32_e32 v30, v30, v8
	v_mul_f32_e32 v31, v31, v8
	v_mul_f32_e32 v20, v4, v20
	v_mul_f32_e32 v21, v5, v21
	v_mul_f32_e32 v30, v2, v30
	v_mul_f32_e32 v31, v3, v31
	v_cvt_pk_bf16_f32 v32, v20, v21
	v_cvt_pk_bf16_f32 v33, v30, v31
	s_add_i32 s14, s50, 28
	s_and_b32 s14, s14, 0xfc
	s_or_b32 s14, s14, s48
	s_mov_b32 s15, s49
	s_lshl_b64 s[14:15], s[14:15], 13
	v_lshl_add_u64 v[10:11], v[0:1], 0, s[14:15]
	global_store_dwordx2 v[10:11], v[32:33], off
	v_lshlrev_b32_e32 v8, 16, v60
	v_lshlrev_b32_e32 v19, 16, v62
	v_and_b32_e32 v29, 0xffff0000, v60
	v_and_b32_e32 v34, 0xffff0000, v62
	v_fma_f32 v20, -v18, v19, v8
	v_fma_f32 v21, -v18, v34, v29
	v_lshlrev_b32_e32 v8, 16, v61
	v_lshlrev_b32_e32 v19, 16, v63
	v_and_b32_e32 v29, 0xffff0000, v61
	v_and_b32_e32 v34, 0xffff0000, v63
	v_fma_f32 v30, -v18, v19, v8
	v_fma_f32 v31, -v18, v34, v29
	v_mul_f32_e32 v8, v21, v21
	v_mul_f32_e32 v19, v31, v31
	v_fmac_f32_e32 v8, v20, v20
	v_fmac_f32_e32 v19, v30, v30
	v_add_f32_e32 v8, v8, v19
	s_nop 1
	v_add_f32_dpp v8, v8, v8 quad_perm:[1,0,3,2] row_mask:0xf bank_mask:0xf
	s_nop 1
	v_add_f32_dpp v8, v8, v8 quad_perm:[2,3,0,1] row_mask:0xf bank_mask:0xf
	s_nop 1
	v_add_f32_dpp v8, v8, v8 row_half_mirror row_mask:0xf bank_mask:0xf
	s_nop 1
	v_add_f32_dpp v8, v8, v8 row_mirror row_mask:0xf bank_mask:0xf
	s_nop 1
	v_readlane_b32 s14, v8, 0
	v_readlane_b32 s15, v8, 16
	v_readlane_b32 s24, v8, 32
	v_readlane_b32 s25, v8, 48
	s_nop 2
	v_mov_b32_e32 v19, s15
	v_mov_b32_e32 v29, s25
	v_add_f32_e32 v19, s14, v19
	v_add_f32_e32 v29, s24, v29
	v_add_f32_e32 v8, v19, v29
	v_fmamk_f32 v8, v8, 0x3b800000, v191
	v_mul_f32_e32 v19, 0x4f800000, v8
	v_cmp_gt_f32_e32 vcc, s76, v8
	s_nop 1
	v_cndmask_b32_e32 v8, v8, v19, vcc
	v_sqrt_f32_e32 v19, v8
	s_nop 0
	v_add_u32_e32 v29, -1, v19
	v_add_u32_e32 v34, 1, v19
	v_fma_f32 v35, -v29, v19, v8
	v_fma_f32 v36, -v34, v19, v8
	v_cmp_ge_f32_e64 s[14:15], 0, v35
	s_nop 1
	v_cndmask_b32_e64 v19, v19, v29, s[14:15]
	v_cmp_lt_f32_e64 s[14:15], 0, v36
	s_nop 1
	v_cndmask_b32_e64 v19, v19, v34, s[14:15]
	v_mul_f32_e32 v29, 0x37800000, v19
	v_cndmask_b32_e32 v19, v19, v29, vcc
	v_cmp_class_f32_e32 vcc, v8, v192
	s_nop 1
	v_cndmask_b32_e32 v8, v19, v8, vcc
	v_div_scale_f32 v19, s[14:15], v8, v8, 1.0
	v_rcp_f32_e32 v34, v19
	v_div_scale_f32 v29, vcc, 1.0, v8, 1.0
	v_fma_f32 v35, -v19, v34, 1.0
	v_fmac_f32_e32 v34, v35, v34
	v_mul_f32_e32 v35, v29, v34
	v_fma_f32 v36, -v19, v35, v29
	v_fmac_f32_e32 v35, v36, v34
	v_fma_f32 v19, -v19, v35, v29
	v_div_fmas_f32 v19, v19, v34, v35
	v_div_fixup_f32 v8, v19, v8, 1.0
	v_mul_f32_e32 v20, v20, v8
	v_mul_f32_e32 v21, v21, v8
	v_mul_f32_e32 v30, v30, v8
	v_mul_f32_e32 v31, v31, v8
	v_mul_f32_e32 v20, v4, v20
	v_mul_f32_e32 v21, v5, v21
	v_mul_f32_e32 v30, v2, v30
	v_mul_f32_e32 v31, v3, v31
	v_cvt_pk_bf16_f32 v32, v20, v21
	v_cvt_pk_bf16_f32 v33, v30, v31
	s_add_u32 s14, s52, 0x3a000
	s_addc_u32 s15, s53, 0
	global_store_dwordx2 v184, v[32:33], s[14:15]
	v_lshlrev_b32_e32 v8, 16, v64
	v_lshlrev_b32_e32 v19, 16, v66
	v_and_b32_e32 v29, 0xffff0000, v64
	v_and_b32_e32 v34, 0xffff0000, v66
	v_fma_f32 v20, -v18, v19, v8
	v_fma_f32 v21, -v18, v34, v29
	v_lshlrev_b32_e32 v8, 16, v65
	v_lshlrev_b32_e32 v19, 16, v67
	v_and_b32_e32 v29, 0xffff0000, v65
	v_and_b32_e32 v34, 0xffff0000, v67
	v_fma_f32 v30, -v18, v19, v8
	v_fma_f32 v31, -v18, v34, v29
	v_mul_f32_e32 v8, v21, v21
	v_mul_f32_e32 v19, v31, v31
	v_fmac_f32_e32 v8, v20, v20
	v_fmac_f32_e32 v19, v30, v30
	v_add_f32_e32 v8, v8, v19
	s_nop 1
	v_add_f32_dpp v8, v8, v8 quad_perm:[1,0,3,2] row_mask:0xf bank_mask:0xf
	s_nop 1
	v_add_f32_dpp v8, v8, v8 quad_perm:[2,3,0,1] row_mask:0xf bank_mask:0xf
	s_nop 1
	v_add_f32_dpp v8, v8, v8 row_half_mirror row_mask:0xf bank_mask:0xf
	s_nop 1
	v_add_f32_dpp v8, v8, v8 row_mirror row_mask:0xf bank_mask:0xf
	s_nop 1
	v_readlane_b32 s14, v8, 0
	v_readlane_b32 s15, v8, 16
	v_readlane_b32 s24, v8, 32
	v_readlane_b32 s25, v8, 48
	s_nop 2
	v_mov_b32_e32 v19, s15
	v_mov_b32_e32 v29, s25
	v_add_f32_e32 v19, s14, v19
	v_add_f32_e32 v29, s24, v29
	v_add_f32_e32 v8, v19, v29
	v_fmamk_f32 v8, v8, 0x3b800000, v191
	v_mul_f32_e32 v19, 0x4f800000, v8
	v_cmp_gt_f32_e32 vcc, s76, v8
	s_nop 1
	v_cndmask_b32_e32 v8, v8, v19, vcc
	v_sqrt_f32_e32 v19, v8
	s_nop 0
	v_add_u32_e32 v29, -1, v19
	v_add_u32_e32 v34, 1, v19
	v_fma_f32 v35, -v29, v19, v8
	v_fma_f32 v36, -v34, v19, v8
	v_cmp_ge_f32_e64 s[14:15], 0, v35
	s_nop 1
	v_cndmask_b32_e64 v19, v19, v29, s[14:15]
	v_cmp_lt_f32_e64 s[14:15], 0, v36
	s_nop 1
	v_cndmask_b32_e64 v19, v19, v34, s[14:15]
	v_mul_f32_e32 v29, 0x37800000, v19
	v_cndmask_b32_e32 v19, v19, v29, vcc
	v_cmp_class_f32_e32 vcc, v8, v192
	s_nop 1
	v_cndmask_b32_e32 v8, v19, v8, vcc
	v_div_scale_f32 v19, s[14:15], v8, v8, 1.0
	v_rcp_f32_e32 v34, v19
	v_div_scale_f32 v29, vcc, 1.0, v8, 1.0
	v_fma_f32 v35, -v19, v34, 1.0
	v_fmac_f32_e32 v34, v35, v34
	v_mul_f32_e32 v35, v29, v34
	v_fma_f32 v36, -v19, v35, v29
	v_fmac_f32_e32 v35, v36, v34
	v_fma_f32 v19, -v19, v35, v29
	v_div_fmas_f32 v19, v19, v34, v35
	v_div_fixup_f32 v8, v19, v8, 1.0
	v_mul_f32_e32 v20, v20, v8
	v_mul_f32_e32 v21, v21, v8
	v_mul_f32_e32 v30, v30, v8
	v_mul_f32_e32 v31, v31, v8
	v_mul_f32_e32 v20, v4, v20
	v_mul_f32_e32 v21, v5, v21
	v_mul_f32_e32 v30, v2, v30
	v_mul_f32_e32 v31, v3, v31
	v_cvt_pk_bf16_f32 v32, v20, v21
	v_cvt_pk_bf16_f32 v33, v30, v31
	s_add_i32 s14, s50, 30
	s_and_b32 s14, s14, 0xfe
	s_or_b32 s14, s14, s48
	s_mov_b32 s15, s49
	s_lshl_b64 s[14:15], s[14:15], 13
	v_lshl_add_u64 v[10:11], v[0:1], 0, s[14:15]
	global_store_dwordx2 v[10:11], v[32:33], off
	v_lshlrev_b32_e32 v8, 16, v68
	v_lshlrev_b32_e32 v19, 16, v70
	v_and_b32_e32 v29, 0xffff0000, v68
	v_and_b32_e32 v34, 0xffff0000, v70
	v_fma_f32 v20, -v18, v19, v8
	v_fma_f32 v21, -v18, v34, v29
	v_lshlrev_b32_e32 v8, 16, v69
	v_lshlrev_b32_e32 v19, 16, v71
	v_and_b32_e32 v29, 0xffff0000, v69
	v_and_b32_e32 v34, 0xffff0000, v71
	v_fma_f32 v30, -v18, v19, v8
	v_fma_f32 v31, -v18, v34, v29
	v_mul_f32_e32 v8, v21, v21
	v_mul_f32_e32 v19, v31, v31
	v_fmac_f32_e32 v8, v20, v20
	v_fmac_f32_e32 v19, v30, v30
	v_add_f32_e32 v8, v8, v19
	s_nop 1
	v_add_f32_dpp v8, v8, v8 quad_perm:[1,0,3,2] row_mask:0xf bank_mask:0xf
	s_nop 1
	v_add_f32_dpp v8, v8, v8 quad_perm:[2,3,0,1] row_mask:0xf bank_mask:0xf
	s_nop 1
	v_add_f32_dpp v8, v8, v8 row_half_mirror row_mask:0xf bank_mask:0xf
	s_nop 1
	v_add_f32_dpp v8, v8, v8 row_mirror row_mask:0xf bank_mask:0xf
	s_nop 1
	v_readlane_b32 s14, v8, 0
	v_readlane_b32 s15, v8, 16
	v_readlane_b32 s24, v8, 32
	v_readlane_b32 s25, v8, 48
	s_nop 2
	v_mov_b32_e32 v19, s15
	v_mov_b32_e32 v29, s25
	v_add_f32_e32 v19, s14, v19
	v_add_f32_e32 v29, s24, v29
	v_add_f32_e32 v8, v19, v29
	v_fmamk_f32 v8, v8, 0x3b800000, v191
	v_mul_f32_e32 v19, 0x4f800000, v8
	v_cmp_gt_f32_e32 vcc, s76, v8
	s_nop 1
	v_cndmask_b32_e32 v8, v8, v19, vcc
	v_sqrt_f32_e32 v19, v8
	s_nop 0
	v_add_u32_e32 v29, -1, v19
	v_add_u32_e32 v34, 1, v19
	v_fma_f32 v35, -v29, v19, v8
	v_fma_f32 v36, -v34, v19, v8
	v_cmp_ge_f32_e64 s[14:15], 0, v35
	s_nop 1
	v_cndmask_b32_e64 v19, v19, v29, s[14:15]
	v_cmp_lt_f32_e64 s[14:15], 0, v36
	s_nop 1
	v_cndmask_b32_e64 v19, v19, v34, s[14:15]
	v_mul_f32_e32 v29, 0x37800000, v19
	v_cndmask_b32_e32 v19, v19, v29, vcc
	v_cmp_class_f32_e32 vcc, v8, v192
	s_nop 1
	v_cndmask_b32_e32 v8, v19, v8, vcc
	v_div_scale_f32 v19, s[14:15], v8, v8, 1.0
	v_rcp_f32_e32 v34, v19
	v_div_scale_f32 v29, vcc, 1.0, v8, 1.0
	v_fma_f32 v35, -v19, v34, 1.0
	v_fmac_f32_e32 v34, v35, v34
	v_mul_f32_e32 v35, v29, v34
	v_fma_f32 v36, -v19, v35, v29
	v_fmac_f32_e32 v35, v36, v34
	v_fma_f32 v19, -v19, v35, v29
	v_div_fmas_f32 v19, v19, v34, v35
	v_div_fixup_f32 v8, v19, v8, 1.0
	v_mul_f32_e32 v20, v20, v8
	v_mul_f32_e32 v21, v21, v8
	v_mul_f32_e32 v30, v30, v8
	v_mul_f32_e32 v31, v31, v8
	v_mul_f32_e32 v20, v4, v20
	v_mul_f32_e32 v21, v5, v21
	v_mul_f32_e32 v30, v2, v30
	v_mul_f32_e32 v31, v3, v31
	v_cvt_pk_bf16_f32 v32, v20, v21
	v_cvt_pk_bf16_f32 v33, v30, v31
	s_add_u32 s14, s52, 0x3e000
	s_addc_u32 s15, s53, 0
	global_store_dwordx2 v184, v[32:33], s[14:15]
	s_mov_b64 s[4:5], 0
	s_branch .LBB0_386
